# ret_out item: K and V row loads issued together with the Q loads (same row base), consumers renamed to registers free in this phase
# speedup vs baseline: 1.0110x; 1.0110x over previous
.LBB0_193:
	v_mul_f32_e32 v0, 0xbfb8aa3b, v65
	v_rndne_f32_e32 v1, v0
	v_sub_f32_e32 v2, v0, v1
	v_fma_f32 v0, v65, s70, -v0
	v_fmac_f32_e32 v0, 0xb2a5705f, v65
	v_add_f32_e32 v0, v2, v0
	v_cvt_i32_f32_e32 v1, v1
	v_exp_f32_e32 v0, v0
	v_cmp_nlt_f32_e32 vcc, s71, v65
	s_ashr_i32 s39, s38, 31
	s_lshl_b64 s[26:27], s[38:39], 14
	v_ldexp_f32 v0, v0, v1
	v_cndmask_b32_e32 v0, 0, v0, vcc
	v_cmp_ngt_f32_e32 vcc, s3, v65
	s_add_u32 s26, s58, s26
	v_ashrrev_i32_e32 v86, 3, v100
	v_cndmask_b32_e32 v2, v238, v0, vcc
	v_add_f32_e32 v3, 1.0, v2
	v_add_f32_e32 v0, -1.0, v3
	v_sub_f32_e32 v1, v0, v3
	v_add_f32_e32 v1, 1.0, v1
	v_sub_f32_e32 v0, v2, v0
	v_add_f32_e32 v4, v0, v1
	v_frexp_mant_f32_e32 v0, v3
	v_cmp_gt_f32_e32 vcc, s5, v0
	v_cvt_f64_f32_e32 v[0:1], v3
	v_frexp_exp_i32_f64_e32 v0, v[0:1]
	v_subbrev_co_u32_e32 v0, vcc, 0, v0, vcc
	v_sub_u32_e32 v1, 0, v0
	v_ldexp_f32 v3, v3, v1
	v_ldexp_f32 v1, v4, v1
	v_add_f32_e32 v4, -1.0, v3
	v_add_f32_e32 v7, 1.0, v3
	v_add_f32_e32 v5, 1.0, v4
	v_add_f32_e32 v15, -1.0, v7
	v_sub_f32_e32 v5, v3, v5
	v_sub_f32_e32 v3, v3, v15
	v_add_f32_e32 v5, v1, v5
	v_add_f32_e32 v1, v1, v3
	v_add_f32_e32 v3, v7, v1
	v_rcp_f32_e32 v15, v3
	v_add_f32_e32 v6, v4, v5
	v_sub_f32_e32 v4, v4, v6
	v_add_f32_e32 v4, v5, v4
	v_sub_f32_e32 v5, v7, v3
	v_add_f32_e32 v1, v1, v5
	v_mul_f32_e32 v5, v6, v15
	v_mul_f32_e32 v7, v3, v5
	v_fma_f32 v17, v5, v3, -v7
	v_fmac_f32_e32 v17, v5, v1
	v_add_f32_e32 v18, v7, v17
	v_sub_f32_e32 v19, v6, v18
	v_sub_f32_e32 v6, v6, v19
	v_sub_f32_e32 v7, v18, v7
	v_sub_f32_e32 v6, v6, v18
	v_add_f32_e32 v4, v4, v6
	v_sub_f32_e32 v6, v7, v17
	v_add_f32_e32 v4, v6, v4
	v_add_f32_e32 v6, v19, v4
	v_mul_f32_e32 v7, v15, v6
	v_mul_f32_e32 v17, v3, v7
	v_fma_f32 v3, v7, v3, -v17
	v_fmac_f32_e32 v3, v7, v1
	v_sub_f32_e32 v1, v19, v6
	v_add_f32_e32 v1, v4, v1
	v_add_f32_e32 v4, v17, v3
	v_sub_f32_e32 v18, v6, v4
	v_sub_f32_e32 v6, v6, v18
	v_sub_f32_e32 v17, v4, v17
	v_sub_f32_e32 v4, v6, v4
	v_add_f32_e32 v1, v1, v4
	v_sub_f32_e32 v3, v17, v3
	v_cvt_f32_i32_e32 v0, v0
	v_add_f32_e32 v1, v3, v1
	v_add_f32_e32 v3, v5, v7
	v_add_f32_e32 v1, v18, v1
	v_sub_f32_e32 v4, v3, v5
	v_mul_f32_e32 v1, v15, v1
	v_sub_f32_e32 v4, v7, v4
	v_add_f32_e32 v1, v4, v1
	v_mul_f32_e32 v7, 0x3f317218, v0
	v_add_f32_e32 v4, v3, v1
	v_fma_f32 v15, v0, s6, -v7
	v_mul_f32_e32 v5, v4, v4
	v_fmac_f32_e32 v15, 0xb102e308, v0
	v_sub_f32_e32 v0, v4, v3
	v_fmamk_f32 v6, v5, 0x3e9b6dac, v222
	v_sub_f32_e32 v0, v1, v0
	v_add_f32_e32 v1, v7, v15
	v_fmaak_f32 v6, v5, v6, 0x3f2aaada
	v_sub_f32_e32 v3, v1, v7
	v_ldexp_f32 v7, v4, 1
	v_mul_f32_e32 v4, v4, v5
	v_mul_f32_e32 v4, v4, v6
	v_add_f32_e32 v5, v7, v4
	v_sub_f32_e32 v6, v5, v7
	v_ldexp_f32 v0, v0, 1
	v_sub_f32_e32 v4, v4, v6
	v_add_f32_e32 v0, v0, v4
	v_add_f32_e32 v4, v5, v0
	v_sub_f32_e32 v5, v4, v5
	v_sub_f32_e32 v0, v0, v5
	v_add_f32_e32 v5, v1, v4
	v_sub_f32_e32 v6, v5, v1
	v_sub_f32_e32 v7, v5, v6
	v_sub_f32_e32 v3, v15, v3
	v_sub_f32_e32 v1, v1, v7
	v_sub_f32_e32 v4, v4, v6
	v_add_f32_e32 v1, v4, v1
	v_add_f32_e32 v4, v3, v0
	v_sub_f32_e32 v6, v4, v3
	v_sub_f32_e32 v7, v4, v6
	v_sub_f32_e32 v3, v3, v7
	v_sub_f32_e32 v0, v0, v6
	v_add_f32_e32 v1, v4, v1
	v_add_f32_e32 v0, v0, v3
	v_add_f32_e32 v3, v5, v1
	v_sub_f32_e32 v4, v3, v5
	v_sub_f32_e32 v1, v1, v4
	v_add_f32_e32 v0, v0, v1
	v_mul_f32_e32 v1, 0xbfb8aa3b, v63
	v_add_f32_e32 v0, v3, v0
	v_rndne_f32_e32 v3, v1
	v_sub_f32_e32 v4, v1, v3
	v_fma_f32 v1, v63, s70, -v1
	v_fmac_f32_e32 v1, 0xb2a5705f, v63
	v_add_f32_e32 v1, v4, v1
	v_exp_f32_e32 v1, v1
	v_cvt_i32_f32_e32 v3, v3
	v_cmp_neq_f32_e32 vcc, s21, v2
	s_addc_u32 s27, s59, s27
	v_ashrrev_i32_e32 v87, 31, v86
	v_cndmask_b32_e32 v0, v238, v0, vcc
	v_cmp_lt_f32_e64 vcc, |v2|, s7
	v_cvt_pk_bf16_f32 v82, v48, v49
	v_cvt_pk_bf16_f32 v83, v46, v47
	v_cvt_pk_bf16_f32 v84, v44, v45
	v_cvt_pk_bf16_f32 v85, v42, v43
	v_cvt_pk_bf16_f32 v40, v40, v41
	s_nop 1
	v_cndmask_b32_e32 v99, v0, v2, vcc
	v_ldexp_f32 v0, v1, v3
	v_cmp_nlt_f32_e32 vcc, s71, v63
	v_cvt_pk_bf16_f32 v41, v38, v39
	v_cvt_pk_bf16_f32 v42, v36, v37
	v_cvt_pk_bf16_f32 v43, v34, v31
	v_and_b32_e32 v101, 15, v100
	v_and_b32_e32 v107, 48, v100
	v_cndmask_b32_e32 v0, 0, v0, vcc
	v_cmp_ngt_f32_e32 vcc, s3, v63
	v_add_u32_e32 v98, s2, v107
	v_or_b32_e32 v116, 64, v101
	v_cndmask_b32_e32 v0, v238, v0, vcc
	v_add_f32_e32 v4, 1.0, v0
	v_add_f32_e32 v1, -1.0, v4
	v_sub_f32_e32 v2, v1, v4
	v_add_f32_e32 v2, 1.0, v2
	v_sub_f32_e32 v1, v0, v1
	v_add_f32_e32 v5, v1, v2
	v_frexp_mant_f32_e32 v1, v4
	v_cvt_f64_f32_e32 v[2:3], v4
	v_cmp_gt_f32_e32 vcc, s5, v1
	v_frexp_exp_i32_f64_e32 v1, v[2:3]
	s_lshl_b32 s88, s22, 1
	v_subbrev_co_u32_e32 v1, vcc, 0, v1, vcc
	v_sub_u32_e32 v2, 0, v1
	v_ldexp_f32 v3, v4, v2
	v_add_f32_e32 v4, -1.0, v3
	v_add_f32_e32 v6, 1.0, v3
	v_ldexp_f32 v2, v5, v2
	v_add_f32_e32 v5, 1.0, v4
	v_add_f32_e32 v7, -1.0, v6
	v_sub_f32_e32 v5, v3, v5
	v_sub_f32_e32 v3, v3, v7
	v_add_f32_e32 v5, v2, v5
	v_add_f32_e32 v2, v2, v3
	v_add_f32_e32 v17, v6, v2
	v_rcp_f32_e32 v3, v17
	v_add_f32_e32 v15, v4, v5
	v_sub_f32_e32 v4, v4, v15
	v_add_f32_e32 v18, v5, v4
	v_sub_f32_e32 v4, v6, v17
	v_add_f32_e32 v19, v2, v4
	v_mul_f32_e32 v2, v15, v3
	v_mul_f32_e32 v33, v17, v2
	v_fma_f32 v35, v2, v17, -v33
	v_fmac_f32_e32 v35, v2, v19
	v_add_f32_e32 v50, v33, v35
	v_sub_f32_e32 v54, v15, v50
	v_sub_f32_e32 v15, v15, v54
	v_sub_f32_e32 v33, v50, v33
	v_sub_f32_e32 v15, v15, v50
	v_add_f32_e32 v15, v18, v15
	v_sub_f32_e32 v18, v33, v35
	v_add_f32_e32 v15, v18, v15
	v_add_f32_e32 v33, v54, v15
	v_mul_f32_e32 v35, v3, v33
	v_mul_f32_e32 v63, v17, v35
	v_sub_f32_e32 v65, v54, v33
	v_lshlrev_b32_e32 v12, 4, v100
	v_fma_f32 v17, v35, v17, -v63
	v_and_b32_e32 v184, 0x70, v12
	v_fmac_f32_e32 v17, v35, v19
	v_lshl_add_u64 v[12:13], s[26:27], 0, v[184:185]
	v_lshlrev_b64 v[18:19], 7, v[86:87]
	v_lshl_add_u64 v[18:19], v[12:13], 0, v[18:19]
	global_load_dwordx4 v[66:69], v[18:19], off
	v_add_u32_e32 v18, 0x100, v100
	v_ashrrev_i32_e32 v88, 3, v18
	v_ashrrev_i32_e32 v89, 31, v88
	v_lshlrev_b64 v[18:19], 7, v[88:89]
	v_lshl_add_u64 v[18:19], v[12:13], 0, v[18:19]
	global_load_dwordx4 v[70:73], v[18:19], off
	v_add_u32_e32 v18, 0x200, v100
	v_ashrrev_i32_e32 v90, 3, v18
	v_ashrrev_i32_e32 v91, 31, v90
	v_lshlrev_b64 v[18:19], 7, v[90:91]
	v_lshl_add_u64 v[18:19], v[12:13], 0, v[18:19]
	global_load_dwordx4 v[74:77], v[18:19], off
	v_add_u32_e32 v18, 0x300, v100
	v_ashrrev_i32_e32 v92, 3, v18
	v_ashrrev_i32_e32 v93, 31, v92
	v_lshlrev_b64 v[18:19], 7, v[92:93]
	v_lshl_add_u64 v[12:13], v[12:13], 0, v[18:19]
	global_load_dwordx4 v[78:81], v[12:13], off
	v_cvt_pk_bf16_f32 v19, v8, v9
	v_cvt_pk_bf16_f32 v8, v10, v11
	v_add_f32_e32 v13, v63, v17
	v_cvt_pk_bf16_f32 v9, v26, v27
	v_cvt_pk_bf16_f32 v10, v28, v29
	v_cvt_pk_bf16_f32 v11, v32, v30
	ds_write_b128 v16, v[8:11] offset:18480
	v_mul_u32_u24_e32 v8, 0x1100, v62
	v_add_f32_e32 v12, v15, v65
	v_sub_f32_e32 v15, v13, v63
	v_sub_f32_e32 v63, v33, v13
	v_mul_u32_u24_e32 v9, 0x21c0, v62
	v_lshlrev_b32_e32 v10, 1, v64
	v_lshlrev_b32_e32 v8, 1, v8
	v_sub_f32_e32 v18, v33, v63
	v_add3_u32 v9, v14, v9, v10
	v_add3_u32 v8, s2, v10, v8
	v_sub_f32_e32 v13, v18, v13
	ds_write_b128 v16, v[82:85] offset:18432
	ds_write_b128 v16, v[40:43] offset:18448
	v_cvt_pk_bf16_f32 v18, v20, v21
	v_cvt_pk_bf16_f32 v20, v22, v23
	v_cvt_pk_bf16_f32 v21, v24, v25
	ds_write_b128 v16, v[18:21] offset:18464
	v_and_b32_e32 v32, 0xffffffe0, v64
	v_or_b32_e32 v105, v32, v101
	v_add_f32_e32 v33, v12, v13
	v_mad_u64_u32 v[12:13], s[26:27], v105, s4, v[98:99]
	v_sub_f32_e32 v15, v15, v17
	v_cvt_f32_i32_e32 v1, v1
	v_cmp_neq_f32_e32 vcc, s21, v0
	v_or_b32_e32 v129, 16, v101
	v_or_b32_e32 v128, 32, v101
	v_mul_f32_e32 v39, 0x3f317218, v1
	v_fma_f32 v40, v1, s6, -v39
	v_fmac_f32_e32 v40, 0xb102e308, v1
	v_or_b32_e32 v127, 48, v101
	v_or_b32_e32 v119, 0x50, v101
	v_or_b32_e32 v117, 0x60, v101
	v_or_b32_e32 v115, 0x70, v101
	s_mov_b32 s36, 0x800000
	s_waitcnt vmcnt(0)
	ds_write_b16 v9, v194 offset:36864
	ds_write_b16_d16_hi v8, v194 offset:37136
	ds_write_b16 v9, v195 offset:37408
	ds_write_b16_d16_hi v9, v195 offset:37680
	ds_write_b16 v9, v196 offset:37952
	ds_write_b16_d16_hi v9, v196 offset:38224
	ds_write_b16 v9, v197 offset:38496
	ds_write_b16_d16_hi v9, v197 offset:38768
	ds_write_b16 v9, v198 offset:39040
	ds_write_b16_d16_hi v9, v198 offset:39312
	ds_write_b16 v9, v199 offset:39584
	ds_write_b16_d16_hi v9, v199 offset:39856
	ds_write_b16 v9, v200 offset:40128
	ds_write_b16_d16_hi v9, v200 offset:40400
	ds_write_b16 v9, v201 offset:40672
	ds_write_b16_d16_hi v9, v201 offset:40944
	ds_write_b16 v9, v206 offset:41216
	ds_write_b16_d16_hi v9, v206 offset:41488
	ds_write_b16 v9, v207 offset:41760
	ds_write_b16_d16_hi v9, v207 offset:42032
	ds_write_b16 v9, v208 offset:42304
	ds_write_b16_d16_hi v9, v208 offset:42576
	ds_write_b16 v9, v209 offset:42848
	ds_write_b16_d16_hi v9, v209 offset:43120
	ds_write_b16 v9, v202 offset:43392
	ds_write_b16_d16_hi v9, v202 offset:43664
	ds_write_b16 v9, v203 offset:43936
	ds_write_b16_d16_hi v9, v203 offset:44208
	ds_write_b16 v9, v204 offset:44480
	ds_write_b16_d16_hi v9, v204 offset:44752
	ds_write_b16 v9, v205 offset:45024
	ds_write_b16_d16_hi v9, v205 offset:45296
	v_add_u32_e32 v4, s2, v184
	v_mad_u64_u32 v[6:7], s[26:27], v86, s4, v[4:5]
	v_add_f32_e32 v8, v15, v33
	v_add_f32_e32 v8, v63, v8
	v_mul_f32_e32 v3, v3, v8
	v_add_f32_e32 v33, v2, v35
	ds_write_b128 v6, v[66:69] offset:54272
	v_mad_u64_u32 v[6:7], s[26:27], v88, s4, v[4:5]
	v_sub_f32_e32 v2, v33, v2
	v_sub_f32_e32 v2, v35, v2
	v_add_f32_e32 v35, v2, v3
	ds_write_b128 v6, v[70:73] offset:54272
	v_mad_u64_u32 v[6:7], s[26:27], v90, s4, v[4:5]
	v_mad_u64_u32 v[4:5], s[26:27], v92, s4, v[4:5]
	v_add_f32_e32 v36, v33, v35
	ds_write_b128 v6, v[74:77] offset:54272
	v_mul_f32_e32 v37, v36, v36
	v_fmamk_f32 v2, v37, 0x3e9b6dac, v222
	v_fmaak_f32 v38, v37, v2, 0x3f2aaada
	v_sub_f32_e32 v1, v36, v33
	v_add_f32_e32 v33, v39, v40
	ds_write_b128 v4, v[78:81] offset:54272
	v_mul_u32_u24_e32 v4, 0x48, v101
	v_lshlrev_b32_e32 v110, 1, v4
	v_add_u32_e32 v34, v98, v110
	s_waitcnt lgkmcnt(0)
	s_barrier
	ds_read_b128 v[24:27], v12
	ds_read_b128 v[28:31], v12 offset:2304
	ds_read_b128 v[4:7], v34 offset:18432
	ds_read_b128 v[20:23], v12 offset:64
	ds_read_b128 v[16:19], v12 offset:2368
	ds_read_b128 v[12:15], v34 offset:18496
	s_waitcnt lgkmcnt(3)
	v_mfma_f32_16x16x32_bf16 v[8:11], v[24:27], v[4:7], 0
	v_sub_f32_e32 v1, v35, v1
	v_ldexp_f32 v1, v1, 1
	v_add3_u32 v107, s2, v110, v107
	v_mfma_f32_16x16x32_bf16 v[4:7], v[28:31], v[4:7], 0
	v_add_u32_e32 v110, 0x1b00, v107
	s_waitcnt lgkmcnt(0)
	v_mfma_f32_16x16x32_bf16 v[92:95], v[20:23], v[12:15], v[8:11]
	s_nop 2
	ds_read_b128 v[8:11], v34 offset:20736
	v_mfma_f32_16x16x32_bf16 v[60:63], v[16:19], v[12:15], v[4:7]
	ds_read_b128 v[12:15], v34 offset:20800
	s_waitcnt lgkmcnt(1)
	v_mfma_f32_16x16x32_bf16 v[2:5], v[24:27], v[8:11], 0
	v_mfma_f32_16x16x32_bf16 v[6:9], v[28:31], v[8:11], 0
	v_sub_f32_e32 v10, v33, v39
	s_waitcnt lgkmcnt(0)
	v_mfma_f32_16x16x32_bf16 v[88:91], v[20:23], v[12:15], v[2:5]
	s_nop 3
	ds_read_b128 v[2:5], v34 offset:23040
	v_mfma_f32_16x16x32_bf16 v[56:59], v[16:19], v[12:15], v[6:9]
	v_sub_f32_e32 v14, v40, v10
	v_mul_f32_e32 v10, v36, v37
	v_mul_f32_e32 v35, v10, v38
	ds_read_b128 v[10:13], v34 offset:23104
	s_waitcnt lgkmcnt(1)
	v_mfma_f32_16x16x32_bf16 v[6:9], v[24:27], v[2:5], 0
	v_ldexp_f32 v15, v36, 1
	v_add_f32_e32 v36, v15, v35
	v_sub_f32_e32 v15, v36, v15
	v_mfma_f32_16x16x32_bf16 v[2:5], v[28:31], v[2:5], 0
	v_sub_f32_e32 v15, v35, v15
	v_add_f32_e32 v1, v1, v15
	v_add_f32_e32 v15, v36, v1
	s_waitcnt lgkmcnt(0)
	v_mfma_f32_16x16x32_bf16 v[84:87], v[20:23], v[10:13], v[6:9]
	v_add_f32_e32 v35, v33, v15
	s_nop 1
	ds_read_b128 v[6:9], v34 offset:25344
	v_mfma_f32_16x16x32_bf16 v[52:55], v[16:19], v[10:13], v[2:5]
	ds_read_b128 v[10:13], v34 offset:25408
	s_nop 1
	v_sub_f32_e32 v2, v15, v36
	v_sub_f32_e32 v1, v1, v2
	s_waitcnt lgkmcnt(1)
	v_mfma_f32_16x16x32_bf16 v[2:5], v[24:27], v[6:9], 0
	v_sub_f32_e32 v36, v35, v33
	v_sub_f32_e32 v37, v35, v36
	v_sub_f32_e32 v33, v33, v37
	v_mfma_f32_16x16x32_bf16 v[6:9], v[28:31], v[6:9], 0
	v_sub_f32_e32 v15, v15, v36
	v_add_f32_e32 v15, v15, v33
	v_mad_u32_u24 v33, v116, s4, v98
	s_waitcnt lgkmcnt(0)
	v_mfma_f32_16x16x32_bf16 v[80:83], v[20:23], v[10:13], v[2:5]
	v_add_f32_e32 v34, v14, v1
	v_lshlrev_b32_e32 v36, 5, v100
	v_and_b32_e32 v104, 32, v36
	ds_read_b128 v[2:5], v33 offset:18432
	v_mfma_f32_16x16x32_bf16 v[48:51], v[16:19], v[10:13], v[6:9]
	v_sub_f32_e32 v10, v34, v14
	v_sub_f32_e32 v11, v34, v10
	v_sub_f32_e32 v14, v14, v11
	v_sub_f32_e32 v1, v1, v10
	ds_read_b128 v[10:13], v33 offset:18496
	s_waitcnt lgkmcnt(1)
	v_mfma_f32_16x16x32_bf16 v[6:9], v[24:27], v[2:5], 0
	v_add_f32_e32 v1, v1, v14
	v_add_f32_e32 v14, v34, v15
	v_add_f32_e32 v15, v35, v14
	s_waitcnt lgkmcnt(0)
	v_mfma_f32_16x16x32_bf16 v[76:79], v[20:23], v[10:13], v[6:9]
	v_lshlrev_b32_e32 v184, 1, v104
	s_movk_i32 s4, 0x110
	s_nop 0
	v_sub_f32_e32 v6, v15, v35
	v_mfma_f32_16x16x32_bf16 v[2:5], v[28:31], v[2:5], 0
	v_sub_f32_e32 v14, v14, v6
	ds_read_b128 v[6:9], v33 offset:20736
	v_add_f32_e32 v1, v1, v14
	v_mfma_f32_16x16x32_bf16 v[44:47], v[16:19], v[10:13], v[2:5]
	ds_read_b128 v[10:13], v33 offset:20800
	v_add_f32_e32 v1, v15, v1
	v_cndmask_b32_e32 v1, v238, v1, vcc
	s_waitcnt lgkmcnt(1)
	v_mfma_f32_16x16x32_bf16 v[2:5], v[24:27], v[6:9], 0
	v_cmp_lt_f32_e64 vcc, |v0|, s7
	s_nop 1
	v_cndmask_b32_e32 v103, v1, v0, vcc
	v_lshrrev_b32_e32 v0, 1, v100
	v_mfma_f32_16x16x32_bf16 v[6:9], v[28:31], v[6:9], 0
	v_bfi_b32 v102, 31, v0, v64
	v_add_u32_e32 v96, s20, v102
	v_ashrrev_i32_e32 v97, 31, v96
	s_waitcnt lgkmcnt(0)
	v_mfma_f32_16x16x32_bf16 v[72:75], v[20:23], v[10:13], v[2:5]
	s_nop 2
	ds_read_b128 v[0:3], v33 offset:23040
	v_lshlrev_b64 v[4:5], 12, v[96:97]
	v_mfma_f32_16x16x32_bf16 v[40:43], v[16:19], v[10:13], v[6:9]
	s_nop 2
	v_lshl_add_u64 v[8:9], s[48:49], 0, v[4:5]
	v_lshl_add_u64 v[34:35], v[8:9], 0, s[88:89]
	ds_read_b128 v[8:11], v33 offset:23104
	s_waitcnt lgkmcnt(1)
	v_mfma_f32_16x16x32_bf16 v[4:7], v[24:27], v[0:3], 0
	v_lshl_add_u64 v[34:35], v[34:35], 0, v[184:185]
	v_mfma_f32_16x16x32_bf16 v[12:15], v[28:31], v[0:3], 0
	s_waitcnt lgkmcnt(0)
	v_mfma_f32_16x16x32_bf16 v[68:71], v[20:23], v[8:11], v[4:7]
	global_load_dwordx4 v[0:3], v[34:35], off offset:1584
	s_nop 2
	global_load_dwordx4 v[4:7], v[34:35], off offset:1568
	ds_read_b128 v[64:67], v33 offset:25344
	v_mfma_f32_16x16x32_bf16 v[36:39], v[16:19], v[8:11], v[12:15]
	global_load_dwordx4 v[8:11], v[34:35], off offset:1552
	s_nop 1
	global_load_dwordx4 v[12:15], v[34:35], off offset:1536
	ds_read_b128 v[130:133], v33 offset:25408
	v_lshrrev_b32_e32 v33, 2, v100
	v_and_or_b32 v100, v33, 12, v32
	v_sub_u32_e32 v32, v100, v101
	v_sub_u32_e32 v33, 0, v32
	v_max_i32_e32 v32, v32, v33
	v_cvt_f32_u32_e32 v106, v32
	s_waitcnt lgkmcnt(1)
	v_mfma_f32_16x16x32_bf16 v[120:123], v[24:27], v[64:67], 0
	v_cmp_lt_i32_e32 vcc, v100, v101
	v_or_b32_e32 v109, 1, v100
	s_waitcnt lgkmcnt(0)
	v_mfma_f32_16x16x32_bf16 v[134:137], v[28:31], v[64:67], 0
	v_cndmask_b32_e32 v108, v99, v103, vcc
	v_mul_f32_e32 v106, v108, v106
	v_mul_f32_e32 v106, 0xbfb8aa3b, v106
	v_mfma_f32_16x16x32_bf16 v[64:67], v[20:23], v[130:133], v[120:123]
	v_sub_u32_e32 v108, v109, v101
	v_sub_u32_e32 v111, 0, v108
	v_max_i32_e32 v108, v108, v111
	v_mfma_f32_16x16x32_bf16 v[32:35], v[16:19], v[130:133], v[134:137]
	v_exp_f32_e32 v130, v106
	v_cvt_f32_u32_e32 v108, v108
	v_cmp_lt_i32_e32 vcc, v109, v101
	s_barrier
	v_mul_f32_e32 v92, v130, v92
	v_bfe_u32 v106, v92, 16, 1
	v_add3_u32 v106, v92, v106, s97
	v_mul_lo_u32 v92, v100, s4
	v_add_u32_e32 v113, s2, v92
	v_cndmask_b32_e32 v92, v99, v103, vcc
	v_mul_f32_e32 v92, v92, v108
	v_mul_f32_e32 v92, 0xbfb8aa3b, v92
	v_exp_f32_e32 v108, v92
	v_lshlrev_b32_e32 v92, 1, v101
	v_add_u32_e32 v118, v113, v92
	v_mul_f32_e32 v93, v108, v93
	v_or_b32_e32 v108, 2, v100
	v_sub_u32_e32 v111, v108, v101
	v_sub_u32_e32 v112, 0, v111
	v_max_i32_e32 v111, v111, v112
	v_cvt_f32_u32_e32 v111, v111
	ds_write_b16_d16_hi v118, v106
	v_bfe_u32 v106, v93, 16, 1
	v_cmp_lt_i32_e32 vcc, v108, v101
	v_add3_u32 v106, v93, v106, s97
	v_add_u32_e32 v114, 0x110, v113
	v_cndmask_b32_e32 v93, v99, v103, vcc
	v_mul_f32_e32 v93, v93, v111
	v_mul_f32_e32 v93, 0xbfb8aa3b, v93
	v_exp_f32_e32 v111, v93
	v_add_u32_e32 v93, v114, v92
	ds_write_b16_d16_hi v93, v106
	v_or_b32_e32 v106, 3, v100
	v_sub_u32_e32 v112, v106, v101
	v_sub_u32_e32 v120, 0, v112
	v_max_i32_e32 v112, v112, v120
	v_cvt_f32_u32_e32 v112, v112
	v_mul_f32_e32 v94, v111, v94
	v_bfe_u32 v111, v94, 16, 1
	v_cmp_lt_i32_e32 vcc, v106, v101
	v_add3_u32 v94, v94, v111, s97
	v_or_b32_e32 v123, 16, v100
	v_cndmask_b32_e32 v111, v99, v103, vcc
	v_mul_f32_e32 v111, v111, v112
	v_mul_f32_e32 v111, 0xbfb8aa3b, v111
	v_exp_f32_e32 v111, v111
	v_add_u32_e32 v112, 0x220, v113
	v_add_u32_e32 v120, v112, v92
	ds_write_b16_d16_hi v120, v94
	v_mul_f32_e32 v94, v111, v95
	v_sub_u32_e32 v111, v100, v129
	v_sub_u32_e32 v121, 0, v111
	v_max_i32_e32 v111, v111, v121
	v_cvt_f32_u32_e32 v111, v111
	v_bfe_u32 v95, v94, 16, 1
	v_cmp_lt_i32_e32 vcc, v100, v129
	v_add3_u32 v95, v94, v95, s97
	v_or_b32_e32 v122, 17, v100
	v_cndmask_b32_e32 v94, v99, v103, vcc
	v_mul_f32_e32 v94, v94, v111
	v_mul_f32_e32 v94, 0xbfb8aa3b, v94
	v_exp_f32_e32 v121, v94
	v_add_u32_e32 v111, 0x330, v113
	v_add_u32_e32 v94, v111, v92
	ds_write_b16_d16_hi v94, v95
	v_mul_f32_e32 v88, v121, v88
	v_bfe_u32 v95, v88, 16, 1
	v_add3_u32 v88, v88, v95, s97
	v_sub_u32_e32 v95, v109, v129
	v_sub_u32_e32 v121, 0, v95
	v_max_i32_e32 v95, v95, v121
	v_cvt_f32_u32_e32 v95, v95
	v_cmp_lt_i32_e32 vcc, v109, v129
	ds_write_b16_d16_hi v118, v88 offset:32
	v_mul_f32_e32 v56, v130, v56
	v_cndmask_b32_e32 v88, v99, v103, vcc
	v_mul_f32_e32 v88, v88, v95
	v_sub_u32_e32 v95, v108, v129
	v_mul_f32_e32 v88, 0xbfb8aa3b, v88
	v_sub_u32_e32 v121, 0, v95
	v_exp_f32_e32 v88, v88
	v_max_i32_e32 v95, v95, v121
	v_cvt_f32_u32_e32 v95, v95
	v_cmp_lt_i32_e32 vcc, v108, v129
	v_mul_f32_e32 v88, v88, v89
	v_or_b32_e32 v121, 18, v100
	v_cndmask_b32_e32 v89, v99, v103, vcc
	v_mul_f32_e32 v89, v89, v95
	v_mul_f32_e32 v89, 0xbfb8aa3b, v89
	v_exp_f32_e32 v89, v89
	v_bfe_u32 v95, v88, 16, 1
	v_add3_u32 v88, v88, v95, s97
	ds_write_b16_d16_hi v93, v88 offset:32
	v_mul_f32_e32 v88, v89, v90
	v_bfe_u32 v89, v88, 16, 1
	v_add3_u32 v88, v88, v89, s97
	v_sub_u32_e32 v89, v106, v129
	v_sub_u32_e32 v90, 0, v89
	v_max_i32_e32 v89, v89, v90
	v_cvt_f32_u32_e32 v89, v89
	v_cmp_lt_i32_e32 vcc, v106, v129
	ds_write_b16_d16_hi v120, v88 offset:32
	s_nop 0
	v_cndmask_b32_e32 v88, v99, v103, vcc
	v_mul_f32_e32 v88, v88, v89
	v_sub_u32_e32 v89, v100, v128
	v_sub_u32_e32 v90, 0, v89
	v_max_i32_e32 v89, v89, v90
	v_cvt_f32_u32_e32 v89, v89
	v_cmp_lt_i32_e32 vcc, v100, v128
	v_mul_f32_e32 v88, 0xbfb8aa3b, v88
	v_exp_f32_e32 v88, v88
	v_cndmask_b32_e32 v90, v99, v103, vcc
	v_mul_f32_e32 v89, v90, v89
	v_mul_f32_e32 v89, 0xbfb8aa3b, v89
	v_exp_f32_e32 v89, v89
	v_mul_f32_e32 v88, v88, v91
	v_bfe_u32 v90, v88, 16, 1
	v_add3_u32 v88, v88, v90, s97
	v_mul_f32_e32 v84, v89, v84
	ds_write_b16_d16_hi v94, v88 offset:32
	v_bfe_u32 v88, v84, 16, 1
	v_add3_u32 v84, v84, v88, s97
	v_sub_u32_e32 v88, v109, v128
	v_sub_u32_e32 v89, 0, v88
	v_max_i32_e32 v88, v88, v89
	v_cvt_f32_u32_e32 v88, v88
	v_cmp_lt_i32_e32 vcc, v109, v128
	ds_write_b16_d16_hi v118, v84 offset:64
	s_nop 0
	v_cndmask_b32_e32 v84, v99, v103, vcc
	v_mul_f32_e32 v84, v84, v88
	v_sub_u32_e32 v88, v108, v128
	v_mul_f32_e32 v84, 0xbfb8aa3b, v84
	v_sub_u32_e32 v89, 0, v88
	v_exp_f32_e32 v84, v84
	v_max_i32_e32 v88, v88, v89
	v_cvt_f32_u32_e32 v88, v88
	v_cmp_lt_i32_e32 vcc, v108, v128
	v_mul_f32_e32 v84, v84, v85
	s_nop 0
	v_cndmask_b32_e32 v85, v99, v103, vcc
	v_mul_f32_e32 v85, v85, v88
	v_mul_f32_e32 v85, 0xbfb8aa3b, v85
	v_exp_f32_e32 v85, v85
	v_bfe_u32 v88, v84, 16, 1
	v_add3_u32 v84, v84, v88, s97
	ds_write_b16_d16_hi v93, v84 offset:64
	v_mul_f32_e32 v84, v85, v86
	v_bfe_u32 v85, v84, 16, 1
	v_add3_u32 v84, v84, v85, s97
	v_sub_u32_e32 v85, v106, v128
	v_sub_u32_e32 v86, 0, v85
	v_max_i32_e32 v85, v85, v86
	v_cvt_f32_u32_e32 v85, v85
	v_cmp_lt_i32_e32 vcc, v106, v128
	ds_write_b16_d16_hi v120, v84 offset:64
	v_add_u32_e32 v88, 0x1200, v107
	v_cndmask_b32_e32 v84, v99, v103, vcc
	v_mul_f32_e32 v84, v84, v85
	v_sub_u32_e32 v85, v100, v127
	v_sub_u32_e32 v86, 0, v85
	v_max_i32_e32 v85, v85, v86
	v_cvt_f32_u32_e32 v85, v85
	v_cmp_lt_i32_e32 vcc, v100, v127
	v_mul_f32_e32 v84, 0xbfb8aa3b, v84
	v_exp_f32_e32 v84, v84
	v_cndmask_b32_e32 v86, v99, v103, vcc
	v_mul_f32_e32 v85, v86, v85
	v_mul_f32_e32 v85, 0xbfb8aa3b, v85
	v_exp_f32_e32 v85, v85
	v_mul_f32_e32 v84, v84, v87
	v_bfe_u32 v86, v84, 16, 1
	v_add3_u32 v84, v84, v86, s97
	v_mul_f32_e32 v80, v85, v80
	ds_write_b16_d16_hi v94, v84 offset:64
	v_bfe_u32 v84, v80, 16, 1
	v_add3_u32 v80, v80, v84, s97
	v_sub_u32_e32 v84, v109, v127
	v_sub_u32_e32 v85, 0, v84
	v_max_i32_e32 v84, v84, v85
	v_cvt_f32_u32_e32 v84, v84
	v_cmp_lt_i32_e32 vcc, v109, v127
	ds_write_b16_d16_hi v118, v80 offset:96
	s_nop 0
	v_cndmask_b32_e32 v80, v99, v103, vcc
	v_mul_f32_e32 v80, v80, v84
	v_sub_u32_e32 v84, v108, v127
	v_mul_f32_e32 v80, 0xbfb8aa3b, v80
	v_sub_u32_e32 v85, 0, v84
	v_exp_f32_e32 v80, v80
	v_max_i32_e32 v84, v84, v85
	v_cvt_f32_u32_e32 v84, v84
	v_cmp_lt_i32_e32 vcc, v108, v127
	v_mul_f32_e32 v80, v80, v81
	s_nop 0
	v_cndmask_b32_e32 v81, v99, v103, vcc
	v_mul_f32_e32 v81, v81, v84
	v_mul_f32_e32 v81, 0xbfb8aa3b, v81
	v_exp_f32_e32 v81, v81
	v_bfe_u32 v84, v80, 16, 1
	v_add3_u32 v80, v80, v84, s97
	ds_write_b16_d16_hi v93, v80 offset:96
	v_mul_f32_e32 v80, v81, v82
	v_bfe_u32 v81, v80, 16, 1
	v_add3_u32 v80, v80, v81, s97
	v_sub_u32_e32 v81, v106, v127
	v_sub_u32_e32 v82, 0, v81
	v_max_i32_e32 v81, v81, v82
	v_cvt_f32_u32_e32 v81, v81
	v_cmp_lt_i32_e32 vcc, v106, v127
	ds_write_b16_d16_hi v120, v80 offset:96
	s_nop 0
	v_cndmask_b32_e32 v80, v99, v103, vcc
	v_mul_f32_e32 v80, v80, v81
	v_sub_u32_e32 v81, v100, v116
	v_sub_u32_e32 v82, 0, v81
	v_max_i32_e32 v81, v81, v82
	v_cvt_f32_u32_e32 v81, v81
	v_cmp_lt_i32_e32 vcc, v100, v116
	v_mul_f32_e32 v80, 0xbfb8aa3b, v80
	v_exp_f32_e32 v80, v80
	v_cndmask_b32_e32 v82, v99, v103, vcc
	v_mul_f32_e32 v81, v82, v81
	v_mul_f32_e32 v81, 0xbfb8aa3b, v81
	v_exp_f32_e32 v81, v81
	v_mul_f32_e32 v80, v80, v83
	v_bfe_u32 v82, v80, 16, 1
	v_add3_u32 v80, v80, v82, s97
	v_mul_f32_e32 v76, v81, v76
	ds_write_b16_d16_hi v94, v80 offset:96
	v_bfe_u32 v80, v76, 16, 1
	v_add3_u32 v76, v76, v80, s97
	v_sub_u32_e32 v80, v109, v116
	v_sub_u32_e32 v81, 0, v80
	v_max_i32_e32 v80, v80, v81
	v_cvt_f32_u32_e32 v80, v80
	v_cmp_lt_i32_e32 vcc, v109, v116
	ds_write_b16_d16_hi v118, v76 offset:128
	s_nop 0
	v_cndmask_b32_e32 v76, v99, v103, vcc
	v_mul_f32_e32 v76, v76, v80
	v_sub_u32_e32 v80, v108, v116
	v_mul_f32_e32 v76, 0xbfb8aa3b, v76
	v_sub_u32_e32 v81, 0, v80
	v_exp_f32_e32 v76, v76
	v_max_i32_e32 v80, v80, v81
	v_cvt_f32_u32_e32 v80, v80
	v_cmp_lt_i32_e32 vcc, v108, v116
	v_mul_f32_e32 v76, v76, v77
	s_nop 0
	v_cndmask_b32_e32 v77, v99, v103, vcc
	v_mul_f32_e32 v77, v77, v80
	v_mul_f32_e32 v77, 0xbfb8aa3b, v77
	v_exp_f32_e32 v77, v77
	v_bfe_u32 v80, v76, 16, 1
	v_add3_u32 v76, v76, v80, s97
	ds_write_b16_d16_hi v93, v76 offset:128
	v_mul_f32_e32 v76, v77, v78
	v_bfe_u32 v77, v76, 16, 1
	v_add3_u32 v76, v76, v77, s97
	v_sub_u32_e32 v77, v106, v116
	v_sub_u32_e32 v78, 0, v77
	v_max_i32_e32 v77, v77, v78
	v_cvt_f32_u32_e32 v77, v77
	v_cmp_lt_i32_e32 vcc, v106, v116
	ds_write_b16_d16_hi v120, v76 offset:128
	s_nop 0
	v_cndmask_b32_e32 v76, v99, v103, vcc
	v_mul_f32_e32 v76, v76, v77
	v_sub_u32_e32 v77, v100, v119
	v_sub_u32_e32 v78, 0, v77
	v_max_i32_e32 v77, v77, v78
	v_cvt_f32_u32_e32 v77, v77
	v_cmp_lt_i32_e32 vcc, v100, v119
	v_mul_f32_e32 v76, 0xbfb8aa3b, v76
	v_exp_f32_e32 v76, v76
	v_cndmask_b32_e32 v78, v99, v103, vcc
	v_mul_f32_e32 v77, v78, v77
	v_mul_f32_e32 v77, 0xbfb8aa3b, v77
	v_exp_f32_e32 v77, v77
	v_mul_f32_e32 v76, v76, v79
	v_bfe_u32 v78, v76, 16, 1
	v_add3_u32 v76, v76, v78, s97
	v_mul_f32_e32 v72, v77, v72
	ds_write_b16_d16_hi v94, v76 offset:128
	v_bfe_u32 v76, v72, 16, 1
	v_add3_u32 v72, v72, v76, s97
	v_sub_u32_e32 v76, v109, v119
	v_sub_u32_e32 v77, 0, v76
	v_max_i32_e32 v76, v76, v77
	v_cvt_f32_u32_e32 v76, v76
	v_cmp_lt_i32_e32 vcc, v109, v119
	ds_write_b16_d16_hi v118, v72 offset:160
	s_nop 0
	v_cndmask_b32_e32 v72, v99, v103, vcc
	v_mul_f32_e32 v72, v72, v76
	v_sub_u32_e32 v76, v108, v119
	v_mul_f32_e32 v72, 0xbfb8aa3b, v72
	v_sub_u32_e32 v77, 0, v76
	v_exp_f32_e32 v72, v72
	v_max_i32_e32 v76, v76, v77
	v_cvt_f32_u32_e32 v76, v76
	v_cmp_lt_i32_e32 vcc, v108, v119
	v_mul_f32_e32 v72, v72, v73
	s_nop 0
	v_cndmask_b32_e32 v73, v99, v103, vcc
	v_mul_f32_e32 v73, v73, v76
	v_mul_f32_e32 v73, 0xbfb8aa3b, v73
	v_exp_f32_e32 v73, v73
	v_bfe_u32 v76, v72, 16, 1
	v_add3_u32 v72, v72, v76, s97
	ds_write_b16_d16_hi v93, v72 offset:160
	v_mul_f32_e32 v72, v73, v74
	v_bfe_u32 v73, v72, 16, 1
	v_add3_u32 v72, v72, v73, s97
	v_sub_u32_e32 v73, v106, v119
	v_sub_u32_e32 v74, 0, v73
	v_max_i32_e32 v73, v73, v74
	v_cvt_f32_u32_e32 v73, v73
	v_cmp_lt_i32_e32 vcc, v106, v119
	ds_write_b16_d16_hi v120, v72 offset:160
	s_nop 0
	v_cndmask_b32_e32 v72, v99, v103, vcc
	v_mul_f32_e32 v72, v72, v73
	v_sub_u32_e32 v73, v100, v117
	v_sub_u32_e32 v74, 0, v73
	v_max_i32_e32 v73, v73, v74
	v_cvt_f32_u32_e32 v73, v73
	v_cmp_lt_i32_e32 vcc, v100, v117
	v_mul_f32_e32 v72, 0xbfb8aa3b, v72
	v_exp_f32_e32 v72, v72
	v_cndmask_b32_e32 v74, v99, v103, vcc
	v_mul_f32_e32 v73, v74, v73
	v_mul_f32_e32 v73, 0xbfb8aa3b, v73
	v_exp_f32_e32 v73, v73
	v_mul_f32_e32 v72, v72, v75
	v_bfe_u32 v74, v72, 16, 1
	v_add3_u32 v72, v72, v74, s97
	v_mul_f32_e32 v68, v73, v68
	ds_write_b16_d16_hi v94, v72 offset:160
	v_bfe_u32 v72, v68, 16, 1
	v_add3_u32 v68, v68, v72, s97
	v_sub_u32_e32 v72, v109, v117
	v_sub_u32_e32 v73, 0, v72
	v_max_i32_e32 v72, v72, v73
	v_cvt_f32_u32_e32 v72, v72
	v_cmp_lt_i32_e32 vcc, v109, v117
	ds_write_b16_d16_hi v118, v68 offset:192
	s_nop 0
	v_cndmask_b32_e32 v68, v99, v103, vcc
	v_mul_f32_e32 v68, v68, v72
	v_sub_u32_e32 v72, v108, v117
	v_mul_f32_e32 v68, 0xbfb8aa3b, v68
	v_sub_u32_e32 v73, 0, v72
	v_exp_f32_e32 v68, v68
	v_max_i32_e32 v72, v72, v73
	v_cvt_f32_u32_e32 v72, v72
	v_cmp_lt_i32_e32 vcc, v108, v117
	v_mul_f32_e32 v68, v68, v69
	s_nop 0
	v_cndmask_b32_e32 v69, v99, v103, vcc
	v_mul_f32_e32 v69, v69, v72
	v_mul_f32_e32 v69, 0xbfb8aa3b, v69
	v_exp_f32_e32 v69, v69
	v_bfe_u32 v72, v68, 16, 1
	v_add3_u32 v68, v68, v72, s97
	ds_write_b16_d16_hi v93, v68 offset:192
	v_mul_f32_e32 v68, v69, v70
	v_bfe_u32 v69, v68, 16, 1
	v_add3_u32 v68, v68, v69, s97
	v_sub_u32_e32 v69, v106, v117
	v_sub_u32_e32 v70, 0, v69
	v_max_i32_e32 v69, v69, v70
	v_cvt_f32_u32_e32 v69, v69
	v_cmp_lt_i32_e32 vcc, v106, v117
	ds_write_b16_d16_hi v120, v68 offset:192
	s_nop 0
	v_cndmask_b32_e32 v68, v99, v103, vcc
	v_mul_f32_e32 v68, v68, v69
	v_sub_u32_e32 v69, v100, v115
	v_sub_u32_e32 v70, 0, v69
	v_max_i32_e32 v69, v69, v70
	v_cvt_f32_u32_e32 v69, v69
	v_cmp_lt_i32_e32 vcc, v100, v115
	v_mul_f32_e32 v68, 0xbfb8aa3b, v68
	v_exp_f32_e32 v68, v68
	v_cndmask_b32_e32 v70, v99, v103, vcc
	v_mul_f32_e32 v69, v70, v69
	v_mul_f32_e32 v69, 0xbfb8aa3b, v69
	v_exp_f32_e32 v69, v69
	v_mul_f32_e32 v68, v68, v71
	v_bfe_u32 v70, v68, 16, 1
	v_add3_u32 v68, v68, v70, s97
	v_mul_f32_e32 v64, v69, v64
	ds_write_b16_d16_hi v94, v68 offset:192
	v_bfe_u32 v68, v64, 16, 1
	v_add3_u32 v64, v64, v68, s97
	v_sub_u32_e32 v68, v109, v115
	v_sub_u32_e32 v69, 0, v68
	v_max_i32_e32 v68, v68, v69
	v_cvt_f32_u32_e32 v68, v68
	v_cmp_lt_i32_e32 vcc, v109, v115
	ds_write_b16_d16_hi v118, v64 offset:224
	v_or_b32_e32 v118, 19, v100
	v_cndmask_b32_e32 v64, v99, v103, vcc
	v_mul_f32_e32 v64, v64, v68
	v_sub_u32_e32 v68, v108, v115
	v_mul_f32_e32 v64, 0xbfb8aa3b, v64
	v_sub_u32_e32 v69, 0, v68
	v_exp_f32_e32 v64, v64
	v_max_i32_e32 v68, v68, v69
	v_cvt_f32_u32_e32 v68, v68
	v_cmp_lt_i32_e32 vcc, v108, v115
	v_mul_f32_e32 v64, v64, v65
	s_nop 0
	v_cndmask_b32_e32 v65, v99, v103, vcc
	v_mul_f32_e32 v65, v65, v68
	v_mul_f32_e32 v65, 0xbfb8aa3b, v65
	v_exp_f32_e32 v65, v65
	v_bfe_u32 v68, v64, 16, 1
	v_add3_u32 v64, v64, v68, s97
	ds_write_b16_d16_hi v93, v64 offset:224
	v_mul_f32_e32 v64, v65, v66
	v_bfe_u32 v65, v64, 16, 1
	v_add3_u32 v64, v64, v65, s97
	v_sub_u32_e32 v65, v106, v115
	v_sub_u32_e32 v66, 0, v65
	v_max_i32_e32 v65, v65, v66
	v_cvt_f32_u32_e32 v65, v65
	v_cmp_lt_i32_e32 vcc, v106, v115
	ds_write_b16_d16_hi v120, v64 offset:224
	v_add_u32_e32 v68, 0x900, v107
	v_cndmask_b32_e32 v64, v99, v103, vcc
	v_mul_f32_e32 v64, v64, v65
	v_sub_u32_e32 v65, v123, v101
	v_sub_u32_e32 v66, 0, v65
	v_max_i32_e32 v65, v65, v66
	v_cvt_f32_u32_e32 v65, v65
	v_cmp_lt_i32_e32 vcc, v123, v101
	v_mul_f32_e32 v64, 0xbfb8aa3b, v64
	v_exp_f32_e32 v64, v64
	v_cndmask_b32_e32 v66, v99, v103, vcc
	v_mul_f32_e32 v65, v66, v65
	v_mul_f32_e32 v65, 0xbfb8aa3b, v65
	v_exp_f32_e32 v65, v65
	v_mul_f32_e32 v64, v64, v67
	v_bfe_u32 v66, v64, 16, 1
	v_add3_u32 v64, v64, v66, s97
	v_mul_f32_e32 v60, v65, v60
	ds_write_b16_d16_hi v94, v64 offset:224
	v_bfe_u32 v64, v60, 16, 1
	v_add3_u32 v64, v60, v64, s97
	v_sub_u32_e32 v60, v122, v101
	v_sub_u32_e32 v65, 0, v60
	v_max_i32_e32 v60, v60, v65
	v_cvt_f32_u32_e32 v60, v60
	v_cmp_lt_i32_e32 vcc, v122, v101
	v_mul_lo_u32 v65, v123, s4
	v_add_u32_e32 v126, s2, v65
	v_cndmask_b32_e32 v66, v99, v103, vcc
	v_mul_f32_e32 v60, v66, v60
	v_mul_f32_e32 v60, 0xbfb8aa3b, v60
	v_exp_f32_e32 v66, v60
	v_sub_u32_e32 v65, v121, v101
	v_add_u32_e32 v60, v126, v92
	ds_write_b16_d16_hi v60, v64
	v_mul_f32_e32 v61, v66, v61
	v_sub_u32_e32 v66, 0, v65
	v_max_i32_e32 v65, v65, v66
	v_cvt_f32_u32_e32 v65, v65
	v_bfe_u32 v64, v61, 16, 1
	v_cmp_lt_i32_e32 vcc, v121, v101
	v_add3_u32 v61, v61, v64, s97
	v_add_u32_e32 v125, 0x110, v126
	v_cndmask_b32_e32 v64, v99, v103, vcc
	v_mul_f32_e32 v64, v64, v65
	v_mul_f32_e32 v64, 0xbfb8aa3b, v64
	v_exp_f32_e32 v65, v64
	v_add_u32_e32 v64, v125, v92
	ds_write_b16_d16_hi v64, v61
	v_cmp_lt_i32_e32 vcc, v118, v101
	v_mul_f32_e32 v61, v65, v62
	v_sub_u32_e32 v65, v118, v101
	v_sub_u32_e32 v66, 0, v65
	v_max_i32_e32 v65, v65, v66
	v_cvt_f32_u32_e32 v65, v65
	v_bfe_u32 v62, v61, 16, 1
	v_add3_u32 v62, v61, v62, s97
	v_cndmask_b32_e32 v61, v99, v103, vcc
	v_mul_f32_e32 v61, v61, v65
	v_mul_f32_e32 v61, 0xbfb8aa3b, v61
	v_exp_f32_e32 v65, v61
	v_add_u32_e32 v124, 0x220, v126
	v_add_u32_e32 v61, v124, v92
	ds_write_b16_d16_hi v61, v62
	v_mul_f32_e32 v62, v65, v63
	v_bfe_u32 v63, v62, 16, 1
	v_add_u32_e32 v120, 0x330, v126
	v_add3_u32 v63, v62, v63, s97
	v_add_u32_e32 v62, v120, v92
	ds_write_b16_d16_hi v62, v63
	v_sub_u32_e32 v63, v122, v129
	v_sub_u32_e32 v65, 0, v63
	v_max_i32_e32 v63, v63, v65
	v_cvt_f32_u32_e32 v63, v63
	v_cmp_lt_i32_e32 vcc, v122, v129
	s_nop 1
	v_cndmask_b32_e32 v65, v99, v103, vcc
	v_mul_f32_e32 v63, v65, v63
	v_mul_f32_e32 v63, 0xbfb8aa3b, v63
	v_exp_f32_e32 v63, v63
	v_bfe_u32 v65, v56, 16, 1
	v_add3_u32 v56, v56, v65, s97
	ds_write_b16_d16_hi v60, v56 offset:32
	v_mul_f32_e32 v56, v63, v57
	v_bfe_u32 v57, v56, 16, 1
	v_add3_u32 v56, v56, v57, s97
	v_sub_u32_e32 v57, v121, v129
	v_sub_u32_e32 v63, 0, v57
	v_max_i32_e32 v57, v57, v63
	v_cvt_f32_u32_e32 v57, v57
	v_cmp_lt_i32_e32 vcc, v121, v129
	ds_write_b16_d16_hi v64, v56 offset:32
	s_nop 0
	v_cndmask_b32_e32 v56, v99, v103, vcc
	v_mul_f32_e32 v56, v56, v57
	v_sub_u32_e32 v57, v118, v129
	v_mul_f32_e32 v56, 0xbfb8aa3b, v56
	v_sub_u32_e32 v63, 0, v57
	v_exp_f32_e32 v56, v56
	v_max_i32_e32 v57, v57, v63
	v_cvt_f32_u32_e32 v57, v57
	v_cmp_lt_i32_e32 vcc, v118, v129
	v_mul_f32_e32 v56, v56, v58
	s_nop 0
	v_cndmask_b32_e32 v58, v99, v103, vcc
	v_mul_f32_e32 v57, v58, v57
	v_mul_f32_e32 v57, 0xbfb8aa3b, v57
	v_exp_f32_e32 v57, v57
	v_bfe_u32 v58, v56, 16, 1
	v_add3_u32 v56, v56, v58, s97
	ds_write_b16_d16_hi v61, v56 offset:32
	v_mul_f32_e32 v56, v57, v59
	v_bfe_u32 v57, v56, 16, 1
	v_add3_u32 v56, v56, v57, s97
	v_sub_u32_e32 v57, v123, v128
	v_sub_u32_e32 v58, 0, v57
	v_max_i32_e32 v57, v57, v58
	v_cvt_f32_u32_e32 v57, v57
	v_cmp_lt_i32_e32 vcc, v123, v128
	ds_write_b16_d16_hi v62, v56 offset:32
	s_nop 0
	v_cndmask_b32_e32 v56, v99, v103, vcc
	v_mul_f32_e32 v56, v56, v57
	v_sub_u32_e32 v57, v122, v128
	v_mul_f32_e32 v56, 0xbfb8aa3b, v56
	v_sub_u32_e32 v58, 0, v57
	v_exp_f32_e32 v56, v56
	v_max_i32_e32 v57, v57, v58
	v_cvt_f32_u32_e32 v57, v57
	v_cmp_lt_i32_e32 vcc, v122, v128
	v_mul_f32_e32 v52, v56, v52
	s_nop 0
	v_cndmask_b32_e32 v56, v99, v103, vcc
	v_mul_f32_e32 v56, v56, v57
	v_mul_f32_e32 v56, 0xbfb8aa3b, v56
	v_exp_f32_e32 v56, v56
	v_bfe_u32 v57, v52, 16, 1
	v_add3_u32 v52, v52, v57, s97
	ds_write_b16_d16_hi v60, v52 offset:64
	v_mul_f32_e32 v52, v56, v53
	v_bfe_u32 v53, v52, 16, 1
	v_add3_u32 v52, v52, v53, s97
	v_sub_u32_e32 v53, v121, v128
	v_sub_u32_e32 v56, 0, v53
	v_max_i32_e32 v53, v53, v56
	v_cvt_f32_u32_e32 v53, v53
	v_cmp_lt_i32_e32 vcc, v121, v128
	ds_write_b16_d16_hi v64, v52 offset:64
	s_nop 0
	v_cndmask_b32_e32 v52, v99, v103, vcc
	v_mul_f32_e32 v52, v52, v53
	v_sub_u32_e32 v53, v118, v128
	v_mul_f32_e32 v52, 0xbfb8aa3b, v52
	v_sub_u32_e32 v56, 0, v53
	v_exp_f32_e32 v52, v52
	v_max_i32_e32 v53, v53, v56
	v_cvt_f32_u32_e32 v53, v53
	v_cmp_lt_i32_e32 vcc, v118, v128
	v_mul_f32_e32 v52, v52, v54
	s_nop 0
	v_cndmask_b32_e32 v54, v99, v103, vcc
	v_mul_f32_e32 v53, v54, v53
	v_mul_f32_e32 v53, 0xbfb8aa3b, v53
	v_exp_f32_e32 v53, v53
	v_bfe_u32 v54, v52, 16, 1
	v_add3_u32 v52, v52, v54, s97
	ds_write_b16_d16_hi v61, v52 offset:64
	v_mul_f32_e32 v52, v53, v55
	v_bfe_u32 v53, v52, 16, 1
	v_add3_u32 v52, v52, v53, s97
	v_sub_u32_e32 v53, v123, v127
	v_sub_u32_e32 v54, 0, v53
	v_max_i32_e32 v53, v53, v54
	v_cvt_f32_u32_e32 v53, v53
	v_cmp_lt_i32_e32 vcc, v123, v127
	ds_write_b16_d16_hi v62, v52 offset:64
	s_nop 0
	v_cndmask_b32_e32 v52, v99, v103, vcc
	v_mul_f32_e32 v52, v52, v53
	v_sub_u32_e32 v53, v122, v127
	v_mul_f32_e32 v52, 0xbfb8aa3b, v52
	v_sub_u32_e32 v54, 0, v53
	v_exp_f32_e32 v52, v52
	v_max_i32_e32 v53, v53, v54
	v_cvt_f32_u32_e32 v53, v53
	v_cmp_lt_i32_e32 vcc, v122, v127
	v_mul_f32_e32 v48, v52, v48
	s_nop 0
	v_cndmask_b32_e32 v52, v99, v103, vcc
	v_mul_f32_e32 v52, v52, v53
	v_mul_f32_e32 v52, 0xbfb8aa3b, v52
	v_exp_f32_e32 v52, v52
	v_bfe_u32 v53, v48, 16, 1
	v_add3_u32 v48, v48, v53, s97
	ds_write_b16_d16_hi v60, v48 offset:96
	v_mul_f32_e32 v48, v52, v49
	v_bfe_u32 v49, v48, 16, 1
	v_add3_u32 v48, v48, v49, s97
	v_sub_u32_e32 v49, v121, v127
	v_sub_u32_e32 v52, 0, v49
	v_max_i32_e32 v49, v49, v52
	v_cvt_f32_u32_e32 v49, v49
	v_cmp_lt_i32_e32 vcc, v121, v127
	ds_write_b16_d16_hi v64, v48 offset:96
	s_nop 0
	v_cndmask_b32_e32 v48, v99, v103, vcc
	v_mul_f32_e32 v48, v48, v49
	v_sub_u32_e32 v49, v118, v127
	v_mul_f32_e32 v48, 0xbfb8aa3b, v48
	v_sub_u32_e32 v52, 0, v49
	v_exp_f32_e32 v48, v48
	v_max_i32_e32 v49, v49, v52
	v_cvt_f32_u32_e32 v49, v49
	v_cmp_lt_i32_e32 vcc, v118, v127
	v_mul_f32_e32 v48, v48, v50
	s_nop 0
	v_cndmask_b32_e32 v50, v99, v103, vcc
	v_mul_f32_e32 v49, v50, v49
	v_mul_f32_e32 v49, 0xbfb8aa3b, v49
	v_exp_f32_e32 v49, v49
	v_bfe_u32 v50, v48, 16, 1
	v_add3_u32 v48, v48, v50, s97
	ds_write_b16_d16_hi v61, v48 offset:96
	v_mul_f32_e32 v48, v49, v51
	v_bfe_u32 v49, v48, 16, 1
	v_add3_u32 v48, v48, v49, s97
	v_sub_u32_e32 v49, v123, v116
	v_sub_u32_e32 v50, 0, v49
	v_max_i32_e32 v49, v49, v50
	v_cvt_f32_u32_e32 v49, v49
	v_cmp_lt_i32_e32 vcc, v123, v116
	ds_write_b16_d16_hi v62, v48 offset:96
	s_nop 0
	v_cndmask_b32_e32 v48, v99, v103, vcc
	v_mul_f32_e32 v48, v48, v49
	v_sub_u32_e32 v49, v122, v116
	v_mul_f32_e32 v48, 0xbfb8aa3b, v48
	v_sub_u32_e32 v50, 0, v49
	v_exp_f32_e32 v48, v48
	v_max_i32_e32 v49, v49, v50
	v_cvt_f32_u32_e32 v49, v49
	v_cmp_lt_i32_e32 vcc, v122, v116
	v_mul_f32_e32 v44, v48, v44
	s_nop 0
	v_cndmask_b32_e32 v48, v99, v103, vcc
	v_mul_f32_e32 v48, v48, v49
	v_mul_f32_e32 v48, 0xbfb8aa3b, v48
	v_exp_f32_e32 v48, v48
	v_bfe_u32 v49, v44, 16, 1
	v_add3_u32 v44, v44, v49, s97
	ds_write_b16_d16_hi v60, v44 offset:128
	v_mul_f32_e32 v44, v48, v45
	v_bfe_u32 v45, v44, 16, 1
	v_add3_u32 v44, v44, v45, s97
	v_sub_u32_e32 v45, v121, v116
	v_sub_u32_e32 v48, 0, v45
	v_max_i32_e32 v45, v45, v48
	v_cvt_f32_u32_e32 v45, v45
	v_cmp_lt_i32_e32 vcc, v121, v116
	ds_write_b16_d16_hi v64, v44 offset:128
	s_nop 0
	v_cndmask_b32_e32 v44, v99, v103, vcc
	v_mul_f32_e32 v44, v44, v45
	v_sub_u32_e32 v45, v118, v116
	v_mul_f32_e32 v44, 0xbfb8aa3b, v44
	v_sub_u32_e32 v48, 0, v45
	v_exp_f32_e32 v44, v44
	v_max_i32_e32 v45, v45, v48
	v_cvt_f32_u32_e32 v45, v45
	v_cmp_lt_i32_e32 vcc, v118, v116
	v_mul_f32_e32 v44, v44, v46
	s_nop 0
	v_cndmask_b32_e32 v46, v99, v103, vcc
	v_mul_f32_e32 v45, v46, v45
	v_mul_f32_e32 v45, 0xbfb8aa3b, v45
	v_exp_f32_e32 v45, v45
	v_bfe_u32 v46, v44, 16, 1
	v_add3_u32 v44, v44, v46, s97
	ds_write_b16_d16_hi v61, v44 offset:128
	v_mul_f32_e32 v44, v45, v47
	v_bfe_u32 v45, v44, 16, 1
	v_add3_u32 v44, v44, v45, s97
	v_sub_u32_e32 v45, v123, v119
	v_sub_u32_e32 v46, 0, v45
	v_max_i32_e32 v45, v45, v46
	v_cvt_f32_u32_e32 v45, v45
	v_cmp_lt_i32_e32 vcc, v123, v119
	ds_write_b16_d16_hi v62, v44 offset:128
	s_nop 0
	v_cndmask_b32_e32 v44, v99, v103, vcc
	v_mul_f32_e32 v44, v44, v45
	v_sub_u32_e32 v45, v122, v119
	v_mul_f32_e32 v44, 0xbfb8aa3b, v44
	v_sub_u32_e32 v46, 0, v45
	v_exp_f32_e32 v44, v44
	v_max_i32_e32 v45, v45, v46
	v_cvt_f32_u32_e32 v45, v45
	v_cmp_lt_i32_e32 vcc, v122, v119
	v_mul_f32_e32 v40, v44, v40
	s_nop 0
	v_cndmask_b32_e32 v44, v99, v103, vcc
	v_mul_f32_e32 v44, v44, v45
	v_mul_f32_e32 v44, 0xbfb8aa3b, v44
	v_exp_f32_e32 v44, v44
	v_bfe_u32 v45, v40, 16, 1
	v_add3_u32 v40, v40, v45, s97
	ds_write_b16_d16_hi v60, v40 offset:160
	v_mul_f32_e32 v40, v44, v41
	v_bfe_u32 v41, v40, 16, 1
	v_add3_u32 v40, v40, v41, s97
	v_sub_u32_e32 v41, v121, v119
	v_sub_u32_e32 v44, 0, v41
	v_max_i32_e32 v41, v41, v44
	v_cvt_f32_u32_e32 v41, v41
	v_cmp_lt_i32_e32 vcc, v121, v119
	ds_write_b16_d16_hi v64, v40 offset:160
	s_nop 0
	v_cndmask_b32_e32 v40, v99, v103, vcc
	v_mul_f32_e32 v40, v40, v41
	v_sub_u32_e32 v41, v118, v119
	v_mul_f32_e32 v40, 0xbfb8aa3b, v40
	v_sub_u32_e32 v44, 0, v41
	v_exp_f32_e32 v40, v40
	v_max_i32_e32 v41, v41, v44
	v_cvt_f32_u32_e32 v41, v41
	v_cmp_lt_i32_e32 vcc, v118, v119
	v_mul_f32_e32 v40, v40, v42
	s_nop 0
	v_cndmask_b32_e32 v42, v99, v103, vcc
	v_mul_f32_e32 v41, v42, v41
	v_mul_f32_e32 v41, 0xbfb8aa3b, v41
	v_exp_f32_e32 v41, v41
	v_bfe_u32 v42, v40, 16, 1
	v_add3_u32 v40, v40, v42, s97
	ds_write_b16_d16_hi v61, v40 offset:160
	v_mul_f32_e32 v40, v41, v43
	v_bfe_u32 v41, v40, 16, 1
	v_add3_u32 v40, v40, v41, s97
	v_sub_u32_e32 v41, v123, v117
	v_sub_u32_e32 v42, 0, v41
	v_max_i32_e32 v41, v41, v42
	v_cvt_f32_u32_e32 v41, v41
	v_cmp_lt_i32_e32 vcc, v123, v117
	ds_write_b16_d16_hi v62, v40 offset:160
	s_nop 0
	v_cndmask_b32_e32 v40, v99, v103, vcc
	v_mul_f32_e32 v40, v40, v41
	v_sub_u32_e32 v41, v122, v117
	v_mul_f32_e32 v40, 0xbfb8aa3b, v40
	v_sub_u32_e32 v42, 0, v41
	v_exp_f32_e32 v40, v40
	v_max_i32_e32 v41, v41, v42
	v_cvt_f32_u32_e32 v41, v41
	v_cmp_lt_i32_e32 vcc, v122, v117
	v_mul_f32_e32 v36, v40, v36
	s_nop 0
	v_cndmask_b32_e32 v40, v99, v103, vcc
	v_mul_f32_e32 v40, v40, v41
	v_mul_f32_e32 v40, 0xbfb8aa3b, v40
	v_exp_f32_e32 v40, v40
	v_bfe_u32 v41, v36, 16, 1
	v_add3_u32 v36, v36, v41, s97
	ds_write_b16_d16_hi v60, v36 offset:192
	v_mul_f32_e32 v36, v40, v37
	v_bfe_u32 v37, v36, 16, 1
	v_add3_u32 v36, v36, v37, s97
	v_sub_u32_e32 v37, v121, v117
	v_sub_u32_e32 v40, 0, v37
	v_max_i32_e32 v37, v37, v40
	v_cvt_f32_u32_e32 v37, v37
	v_cmp_lt_i32_e32 vcc, v121, v117
	ds_write_b16_d16_hi v64, v36 offset:192
	s_nop 0
	v_cndmask_b32_e32 v36, v99, v103, vcc
	v_mul_f32_e32 v36, v36, v37
	v_sub_u32_e32 v37, v118, v117
	v_mul_f32_e32 v36, 0xbfb8aa3b, v36
	v_sub_u32_e32 v40, 0, v37
	v_exp_f32_e32 v36, v36
	v_max_i32_e32 v37, v37, v40
	v_cvt_f32_u32_e32 v37, v37
	v_cmp_lt_i32_e32 vcc, v118, v117
	v_mul_f32_e32 v36, v36, v38
	v_mad_u64_u32 v[116:117], s[22:23], v105, s4, v[98:99]
	v_cndmask_b32_e32 v38, v99, v103, vcc
	v_mul_f32_e32 v37, v38, v37
	v_mul_f32_e32 v37, 0xbfb8aa3b, v37
	v_exp_f32_e32 v37, v37
	v_bfe_u32 v38, v36, 16, 1
	v_add3_u32 v36, v36, v38, s97
	ds_write_b16_d16_hi v61, v36 offset:192
	v_mul_f32_e32 v36, v37, v39
	v_bfe_u32 v37, v36, 16, 1
	v_add3_u32 v36, v36, v37, s97
	v_sub_u32_e32 v37, v123, v115
	v_sub_u32_e32 v38, 0, v37
	v_max_i32_e32 v37, v37, v38
	v_cvt_f32_u32_e32 v37, v37
	v_cmp_lt_i32_e32 vcc, v123, v115
	ds_write_b16_d16_hi v62, v36 offset:192
	s_nop 0
	v_cndmask_b32_e32 v36, v99, v103, vcc
	v_mul_f32_e32 v36, v36, v37
	v_sub_u32_e32 v37, v122, v115
	v_mul_f32_e32 v36, 0xbfb8aa3b, v36
	v_sub_u32_e32 v38, 0, v37
	v_exp_f32_e32 v36, v36
	v_max_i32_e32 v37, v37, v38
	v_cvt_f32_u32_e32 v37, v37
	v_cmp_lt_i32_e32 vcc, v122, v115
	v_mul_f32_e32 v32, v36, v32
	s_nop 0
	v_cndmask_b32_e32 v36, v99, v103, vcc
	v_mul_f32_e32 v36, v36, v37
	v_mul_f32_e32 v36, 0xbfb8aa3b, v36
	v_exp_f32_e32 v36, v36
	v_bfe_u32 v37, v32, 16, 1
	v_add3_u32 v32, v32, v37, s97
	ds_write_b16_d16_hi v60, v32 offset:224
	v_mul_f32_e32 v32, v36, v33
	v_bfe_u32 v33, v32, 16, 1
	v_add3_u32 v32, v32, v33, s97
	v_sub_u32_e32 v33, v121, v115
	v_sub_u32_e32 v36, 0, v33
	v_max_i32_e32 v33, v33, v36
	v_cvt_f32_u32_e32 v33, v33
	v_cmp_lt_i32_e32 vcc, v121, v115
	ds_write_b16_d16_hi v64, v32 offset:224
	s_nop 0
	v_cndmask_b32_e32 v32, v99, v103, vcc
	v_mul_f32_e32 v32, v32, v33
	v_sub_u32_e32 v33, v118, v115
	v_mul_f32_e32 v32, 0xbfb8aa3b, v32
	v_sub_u32_e32 v36, 0, v33
	v_exp_f32_e32 v32, v32
	v_max_i32_e32 v33, v33, v36
	v_cvt_f32_u32_e32 v33, v33
	v_cmp_lt_i32_e32 vcc, v118, v115
	v_mul_f32_e32 v32, v32, v34
	s_nop 0
	v_cndmask_b32_e32 v34, v99, v103, vcc
	v_mul_f32_e32 v33, v34, v33
	v_mul_f32_e32 v33, 0xbfb8aa3b, v33
	v_exp_f32_e32 v33, v33
	v_bfe_u32 v34, v32, 16, 1
	v_add3_u32 v32, v32, v34, s97
	ds_write_b16_d16_hi v61, v32 offset:224
	v_mul_f32_e32 v32, v33, v35
	v_bfe_u32 v33, v32, 16, 1
	v_add3_u32 v32, v32, v33, s97
	ds_write_b16_d16_hi v62, v32 offset:224
	s_waitcnt lgkmcnt(0)
	s_barrier
	ds_read_b128 v[32:35], v107 offset:54272
	ds_read_b128 v[48:51], v107 offset:54336
	ds_read_b128 v[40:43], v107 offset:63488
	ds_read_b128 v[52:55], v107 offset:63552
	s_waitcnt lgkmcnt(3)
	v_mfma_f32_16x16x32_bf16 v[36:39], v[24:27], v[32:35], 0
	ds_read_b128 v[72:75], v107 offset:56640
	ds_read_b128 v[76:79], v68 offset:63552
	ds_read_b128 v[84:87], v107 offset:58944
	s_waitcnt lgkmcnt(4)
	v_mfma_f32_16x16x32_bf16 v[44:47], v[24:27], v[40:43], 0
	ds_read_b128 v[128:131], v107 offset:61248
	ds_read_b128 v[148:151], v116 offset:64
	ds_read_b128 v[144:147], v116 offset:4352
	v_mfma_f32_16x16x32_bf16 v[32:35], v[28:31], v[32:35], 0
	ds_read_b128 v[164:167], v116 offset:4544
	v_cmp_lt_i32_e32 vcc, v235, v229
	v_mfma_f32_16x16x32_bf16 v[40:43], v[28:31], v[40:43], 0
	v_mfma_f32_16x16x32_bf16 v[56:59], v[20:23], v[48:51], v[36:39]
	v_mfma_f32_16x16x32_bf16 v[36:39], v[16:19], v[48:51], v[32:35]
	ds_read_b128 v[48:51], v68 offset:63488
	s_waitcnt lgkmcnt(8)
	v_mfma_f32_16x16x32_bf16 v[32:35], v[16:19], v[52:55], v[40:43]
	s_nop 2
	ds_read_b128 v[40:43], v107 offset:56576
	v_mfma_f32_16x16x32_bf16 v[60:63], v[20:23], v[52:55], v[44:47]
	s_waitcnt lgkmcnt(0)
	v_mfma_f32_16x16x32_bf16 v[44:47], v[24:27], v[40:43], 0
	v_mfma_f32_16x16x32_bf16 v[52:55], v[24:27], v[48:51], 0
	v_mfma_f32_16x16x32_bf16 v[40:43], v[28:31], v[40:43], 0
	v_mfma_f32_16x16x32_bf16 v[48:51], v[28:31], v[48:51], 0
	v_mfma_f32_16x16x32_bf16 v[64:67], v[20:23], v[72:75], v[44:47]
	v_mfma_f32_16x16x32_bf16 v[44:47], v[16:19], v[72:75], v[40:43]
	ds_read_b128 v[72:75], v88 offset:63488
	ds_read_b128 v[88:91], v88 offset:63552
	v_mfma_f32_16x16x32_bf16 v[40:43], v[16:19], v[76:79], v[48:51]
	s_nop 2
	ds_read_b128 v[48:51], v107 offset:58880
	v_mfma_f32_16x16x32_bf16 v[68:71], v[20:23], v[76:79], v[52:55]
	s_waitcnt lgkmcnt(0)
	v_mfma_f32_16x16x32_bf16 v[52:55], v[24:27], v[48:51], 0
	v_mfma_f32_16x16x32_bf16 v[48:51], v[28:31], v[48:51], 0
	v_mfma_f32_16x16x32_bf16 v[80:83], v[28:31], v[72:75], 0
	v_mfma_f32_16x16x32_bf16 v[76:79], v[24:27], v[72:75], 0
	v_mfma_f32_16x16x32_bf16 v[72:75], v[20:23], v[84:87], v[52:55]
	v_mfma_f32_16x16x32_bf16 v[52:55], v[16:19], v[84:87], v[48:51]
	v_mfma_f32_16x16x32_bf16 v[48:51], v[16:19], v[88:91], v[80:83]
	s_nop 3
	ds_read_b128 v[80:83], v107 offset:61184
	v_mfma_f32_16x16x32_bf16 v[76:79], v[20:23], v[88:91], v[76:79]
	ds_read_b128 v[88:91], v110 offset:63488
	s_waitcnt lgkmcnt(1)
	v_mfma_f32_16x16x32_bf16 v[84:87], v[24:27], v[80:83], 0
	s_waitcnt lgkmcnt(0)
	v_mfma_f32_16x16x32_bf16 v[92:95], v[24:27], v[88:91], 0
	v_mfma_f32_16x16x32_bf16 v[24:27], v[20:23], v[128:131], v[84:87]
	s_nop 4
	ds_read_b128 v[84:87], v110 offset:63552
	v_mfma_f32_16x16x32_bf16 v[80:83], v[28:31], v[80:83], 0
	v_mfma_f32_16x16x32_bf16 v[88:91], v[28:31], v[88:91], 0
	s_waitcnt lgkmcnt(0)
	v_mfma_f32_16x16x32_bf16 v[28:31], v[20:23], v[84:87], v[92:95]
	v_mfma_f32_16x16x32_bf16 v[20:23], v[16:19], v[128:131], v[80:83]
	s_nop 3
	ds_read_b128 v[80:83], v116
	v_mfma_f32_16x16x32_bf16 v[16:19], v[16:19], v[84:87], v[88:91]
	v_mul_u32_u24_e32 v84, 0x88, v101
	v_lshl_add_u32 v98, v84, 1, v98
	ds_read_b128 v[84:87], v98 offset:36864
	ds_read_b128 v[92:95], v98 offset:41216
	ds_read_b128 v[132:135], v98 offset:45568
	ds_read_b128 v[156:159], v98 offset:45632
	ds_read_b128 v[140:143], v98 offset:49920
	ds_read_b128 v[160:163], v98 offset:49984
	s_waitcnt lgkmcnt(5)
	v_mfma_f32_16x16x32_bf16 v[88:91], v[80:83], v[84:87], 0
	ds_read_b128 v[152:155], v98 offset:41280
	s_waitcnt lgkmcnt(5)
	v_mfma_f32_16x16x32_bf16 v[128:131], v[80:83], v[92:95], 0
	s_waitcnt lgkmcnt(4)
	v_mfma_f32_16x16x32_bf16 v[136:139], v[80:83], v[132:135], 0
	s_waitcnt lgkmcnt(2)
	v_mfma_f32_16x16x32_bf16 v[80:83], v[80:83], v[140:143], 0
	v_mfma_f32_16x16x32_bf16 v[84:87], v[144:147], v[84:87], 0
	v_mfma_f32_16x16x32_bf16 v[92:95], v[144:147], v[92:95], 0
	v_mfma_f32_16x16x32_bf16 v[132:135], v[144:147], v[132:135], 0
	v_mfma_f32_16x16x32_bf16 v[140:143], v[144:147], v[140:143], 0
	ds_read_b128 v[144:147], v98 offset:36928
	s_waitcnt lgkmcnt(0)
	v_mfma_f32_16x16x32_bf16 v[88:91], v[148:151], v[144:147], v[88:91]
	v_mfma_f32_16x16x32_bf16 v[128:131], v[148:151], v[152:155], v[128:131]
	v_mfma_f32_16x16x32_bf16 v[136:139], v[148:151], v[156:159], v[136:139]
	v_mfma_f32_16x16x32_bf16 v[80:83], v[148:151], v[160:163], v[80:83]
	ds_read_b128 v[148:151], v116 offset:4416
	s_waitcnt lgkmcnt(0)
	v_mfma_f32_16x16x32_bf16 v[84:87], v[148:151], v[144:147], v[84:87]
	ds_read_b128 v[144:147], v116 offset:128
	v_mfma_f32_16x16x32_bf16 v[92:95], v[148:151], v[152:155], v[92:95]
	ds_read_b128 v[152:155], v98 offset:41344
	v_mfma_f32_16x16x32_bf16 v[132:135], v[148:151], v[156:159], v[132:135]
	ds_read_b128 v[156:159], v98 offset:45696
	v_mfma_f32_16x16x32_bf16 v[140:143], v[148:151], v[160:163], v[140:143]
	ds_read_b128 v[148:151], v98 offset:36992
	ds_read_b128 v[160:163], v98 offset:50048
	s_waitcnt lgkmcnt(1)
	v_mfma_f32_16x16x32_bf16 v[88:91], v[144:147], v[148:151], v[88:91]
	v_mfma_f32_16x16x32_bf16 v[128:131], v[144:147], v[152:155], v[128:131]
	v_mfma_f32_16x16x32_bf16 v[136:139], v[144:147], v[156:159], v[136:139]
	s_waitcnt lgkmcnt(0)
	v_mfma_f32_16x16x32_bf16 v[80:83], v[144:147], v[160:163], v[80:83]
	ds_read_b128 v[144:147], v116 offset:4480
	s_waitcnt lgkmcnt(0)
	v_mfma_f32_16x16x32_bf16 v[84:87], v[144:147], v[148:151], v[84:87]
	ds_read_b128 v[148:151], v116 offset:192
	v_mfma_f32_16x16x32_bf16 v[92:95], v[144:147], v[152:155], v[92:95]
	v_mfma_f32_16x16x32_bf16 v[132:135], v[144:147], v[156:159], v[132:135]
	ds_read_b128 v[156:159], v98 offset:45760
	v_mfma_f32_16x16x32_bf16 v[140:143], v[144:147], v[160:163], v[140:143]
	ds_read_b128 v[144:147], v98 offset:37056
	ds_read_b128 v[160:163], v98 offset:50112
	s_waitcnt lgkmcnt(1)
	v_mfma_f32_16x16x32_bf16 v[152:155], v[148:151], v[144:147], v[88:91]
	s_nop 2
	ds_read_b128 v[88:91], v98 offset:41408
	s_waitcnt lgkmcnt(0)
	v_mfma_f32_16x16x32_bf16 v[128:131], v[148:151], v[88:91], v[128:131]
	v_mfma_f32_16x16x32_bf16 v[88:91], v[164:167], v[88:91], v[92:95]
	s_nop 2
	v_cvt_f32_i32_e32 v92, v109
	v_sub_u32_e32 v93, 0x80, v100
	v_cvt_f32_i32_e32 v93, v93
	v_mfma_f32_16x16x32_bf16 v[136:139], v[148:151], v[156:159], v[136:139]
	v_mul_f32_e32 v92, v92, v99
	v_mul_f32_e32 v92, 0xbfb8aa3b, v92
	v_exp_f32_e32 v98, v92
	v_mul_f32_e32 v92, v93, v103
	v_mul_f32_e32 v92, 0xbfb8aa3b, v92
	v_exp_f32_e32 v105, v92
	v_fma_f32 v56, v98, v56, v152
	v_fma_f32 v64, v98, v64, v128
	v_mfma_f32_16x16x32_bf16 v[148:151], v[148:151], v[160:163], v[80:83]
	v_fmac_f32_e32 v56, v105, v60
	v_lshlrev_b32_e32 v60, 2, v101
	v_add_u32_e32 v101, v113, v60
	v_fmac_f32_e32 v64, v105, v68
	ds_write2_b32 v101, v56, v64 offset1:16
	v_cvt_f32_i32_e32 v64, v108
	v_sub_u32_e32 v68, 0x80, v109
	v_cvt_f32_i32_e32 v68, v68
	v_fma_f32 v56, v98, v72, v136
	v_mul_f32_e32 v64, v64, v99
	v_mul_f32_e32 v64, 0xbfb8aa3b, v64
	v_mul_f32_e32 v68, v68, v103
	v_exp_f32_e32 v64, v64
	v_mul_f32_e32 v68, 0xbfb8aa3b, v68
	v_exp_f32_e32 v68, v68
	v_fma_f32 v24, v98, v24, v148
	v_fmac_f32_e32 v56, v105, v76
	v_fmac_f32_e32 v24, v105, v28
	ds_write2_b32 v101, v56, v24 offset0:32 offset1:48
	v_fma_f32 v24, v64, v57, v153
	v_fma_f32 v56, v64, v65, v129
	v_fmac_f32_e32 v24, v68, v61
	v_add_u32_e32 v28, v114, v60
	v_fmac_f32_e32 v56, v68, v69
	ds_write2_b32 v28, v24, v56 offset1:16
	v_cvt_f32_i32_e32 v56, v106
	v_sub_u32_e32 v57, 0x80, v108
	v_cvt_f32_i32_e32 v57, v57
	v_fma_f32 v24, v64, v73, v137
	v_mul_f32_e32 v56, v56, v99
	v_mul_f32_e32 v56, 0xbfb8aa3b, v56
	v_mul_f32_e32 v57, v57, v103
	v_exp_f32_e32 v56, v56
	v_mul_f32_e32 v57, 0xbfb8aa3b, v57
	v_exp_f32_e32 v57, v57
	v_fma_f32 v25, v64, v25, v149
	v_fmac_f32_e32 v24, v68, v77
	v_fmac_f32_e32 v25, v68, v29
	ds_write2_b32 v28, v24, v25 offset0:32 offset1:48
	v_fma_f32 v24, v56, v58, v154
	v_fma_f32 v28, v56, v66, v130
	v_fmac_f32_e32 v24, v57, v62
	v_add_u32_e32 v25, v112, v60
	v_fmac_f32_e32 v28, v57, v70
	ds_write2_b32 v25, v24, v28 offset1:16
	v_add_u32_e32 v28, 4, v100
	v_fma_f32 v24, v56, v74, v138
	v_cvt_f32_i32_e32 v28, v28
	v_fma_f32 v26, v56, v26, v150
	v_sub_u32_e32 v29, 0x80, v106
	v_fmac_f32_e32 v24, v57, v78
	v_cvt_f32_i32_e32 v29, v29
	v_fmac_f32_e32 v26, v57, v30
	ds_write2_b32 v25, v24, v26 offset0:32 offset1:48
	v_cvt_f32_i32_e32 v25, v122
	v_sub_u32_e32 v26, 0x80, v123
	v_cvt_f32_i32_e32 v26, v26
	v_mul_f32_e32 v28, v28, v99
	v_mul_f32_e32 v28, 0xbfb8aa3b, v28
	v_mul_f32_e32 v29, v29, v103
	v_exp_f32_e32 v28, v28
	v_mul_f32_e32 v29, 0xbfb8aa3b, v29
	v_mul_f32_e32 v25, v25, v99
	v_exp_f32_e32 v29, v29
	v_mul_f32_e32 v25, 0xbfb8aa3b, v25
	v_mul_f32_e32 v26, v26, v103
	v_mfma_f32_16x16x32_bf16 v[84:87], v[164:167], v[144:147], v[84:87]
	v_exp_f32_e32 v25, v25
	v_mul_f32_e32 v26, 0xbfb8aa3b, v26
	v_exp_f32_e32 v26, v26
	v_mfma_f32_16x16x32_bf16 v[80:83], v[164:167], v[156:159], v[132:135]
	v_fmac_f32_e32 v155, v28, v59
	v_fmac_f32_e32 v131, v28, v67
	v_fmac_f32_e32 v139, v28, v75
	v_mfma_f32_16x16x32_bf16 v[92:95], v[164:167], v[160:163], v[140:143]
	v_fmac_f32_e32 v151, v28, v27
	v_fmac_f32_e32 v155, v29, v63
	v_add_u32_e32 v24, v111, v60
	v_fmac_f32_e32 v131, v29, v71
	v_fmac_f32_e32 v139, v29, v79
	v_fmac_f32_e32 v151, v29, v31
	ds_write2_b32 v24, v155, v131 offset1:16
	ds_write2_b32 v24, v139, v151 offset0:32 offset1:48
	v_fma_f32 v24, v25, v36, v84
	v_fma_f32 v28, v25, v44, v88
	v_fmac_f32_e32 v24, v26, v32
	v_add_u32_e32 v27, v126, v60
	v_fmac_f32_e32 v28, v26, v40
	ds_write2_b32 v27, v24, v28 offset1:16
	v_fma_f32 v24, v25, v52, v80
	v_cvt_f32_i32_e32 v28, v121
	v_fma_f32 v20, v25, v20, v92
	v_sub_u32_e32 v25, 0x80, v122
	v_cvt_f32_i32_e32 v25, v25
	v_mul_f32_e32 v28, v28, v99
	v_mul_f32_e32 v28, 0xbfb8aa3b, v28
	v_exp_f32_e32 v28, v28
	v_mul_f32_e32 v25, v25, v103
	v_mul_f32_e32 v25, 0xbfb8aa3b, v25
	v_exp_f32_e32 v25, v25
	v_fmac_f32_e32 v24, v26, v48
	v_fmac_f32_e32 v20, v26, v16
	ds_write2_b32 v27, v24, v20 offset0:32 offset1:48
	v_fma_f32 v16, v28, v37, v85
	v_fma_f32 v24, v28, v45, v89
	v_fmac_f32_e32 v16, v25, v33
	v_add_u32_e32 v20, v125, v60
	v_fmac_f32_e32 v24, v25, v41
	ds_write2_b32 v20, v16, v24 offset1:16
	v_cvt_f32_i32_e32 v24, v118
	v_sub_u32_e32 v26, 0x80, v121
	v_cvt_f32_i32_e32 v26, v26
	v_fma_f32 v16, v28, v53, v81
	v_mul_f32_e32 v24, v24, v99
	v_mul_f32_e32 v24, 0xbfb8aa3b, v24
	v_mul_f32_e32 v26, v26, v103
	v_exp_f32_e32 v24, v24
	v_mul_f32_e32 v26, 0xbfb8aa3b, v26
	v_exp_f32_e32 v26, v26
	v_fma_f32 v21, v28, v21, v93
	v_fmac_f32_e32 v16, v25, v49
	v_fmac_f32_e32 v21, v25, v17
	ds_write2_b32 v20, v16, v21 offset0:32 offset1:48
	v_fma_f32 v16, v24, v38, v86
	v_fma_f32 v20, v24, v46, v90
	v_fmac_f32_e32 v16, v26, v34
	v_add_u32_e32 v17, v124, v60
	v_fmac_f32_e32 v20, v26, v42
	ds_write2_b32 v17, v16, v20 offset1:16
	v_add_u32_e32 v20, 20, v100
	v_cvt_f32_i32_e32 v20, v20
	v_fma_f32 v21, v24, v22, v94
	v_sub_u32_e32 v22, 0x80, v118
	v_cvt_f32_i32_e32 v22, v22
	v_mul_f32_e32 v20, v20, v99
	v_mul_f32_e32 v20, 0xbfb8aa3b, v20
	v_exp_f32_e32 v20, v20
	v_mul_f32_e32 v22, v22, v103
	v_mul_f32_e32 v22, 0xbfb8aa3b, v22
	v_exp_f32_e32 v22, v22
	v_fma_f32 v16, v24, v54, v82
	v_fmac_f32_e32 v16, v26, v50
	v_fmac_f32_e32 v21, v26, v18
	v_fmac_f32_e32 v87, v20, v39
	v_fmac_f32_e32 v91, v20, v47
	v_fmac_f32_e32 v83, v20, v55
	v_fmac_f32_e32 v95, v20, v23
	ds_write2_b32 v17, v16, v21 offset0:32 offset1:48
	v_fmac_f32_e32 v87, v22, v35
	v_add_u32_e32 v16, v120, v60
	v_fmac_f32_e32 v91, v22, v43
	v_fmac_f32_e32 v83, v22, v51
	v_fmac_f32_e32 v95, v22, v19
	ds_write2_b32 v16, v87, v91 offset1:16
	ds_write2_b32 v16, v83, v95 offset0:32 offset1:48
	v_mul_lo_u32 v16, v102, s4
	v_lshlrev_b32_e32 v17, 2, v104
	v_add3_u32 v44, s2, v16, v17
	s_waitcnt lgkmcnt(0)
	s_barrier
	ds_read_b128 v[36:39], v44
	ds_read_b128 v[32:35], v44 offset:16
	ds_read_b128 v[28:31], v44 offset:32
	ds_read_b128 v[24:27], v44 offset:48
	ds_read_b128 v[20:23], v44 offset:64
	ds_read_b128 v[16:19], v44 offset:80
	s_waitcnt lgkmcnt(5)
	v_add_f32_e32 v40, 0, v36
	v_add_f32_e32 v40, v40, v37
	v_add_f32_e32 v40, v40, v38
	v_add_f32_e32 v40, v40, v39
	s_waitcnt lgkmcnt(4)
	v_add_f32_e32 v40, v40, v32
	v_add_f32_e32 v40, v40, v33
	v_add_f32_e32 v40, v40, v34
	v_add_f32_e32 v40, v40, v35
	s_waitcnt lgkmcnt(3)
	v_add_f32_e32 v40, v40, v28
	v_add_f32_e32 v40, v40, v29
	v_add_f32_e32 v40, v40, v30
	v_add_f32_e32 v40, v40, v31
	s_waitcnt lgkmcnt(2)
	v_add_f32_e32 v40, v40, v24
	v_add_f32_e32 v40, v40, v25
	v_add_f32_e32 v40, v40, v26
	v_add_f32_e32 v40, v40, v27
	s_waitcnt lgkmcnt(1)
	v_add_f32_e32 v40, v40, v20
	v_add_f32_e32 v40, v40, v21
	v_add_f32_e32 v40, v40, v22
	v_add_f32_e32 v40, v40, v23
	s_waitcnt lgkmcnt(0)
	v_add_f32_e32 v40, v40, v16
	v_add_f32_e32 v48, v40, v17
	ds_read_b128 v[40:43], v44 offset:96
	v_cndmask_b32_e32 v45, v228, v235, vcc
	v_add_f32_e32 v48, v48, v18
	v_lshlrev_b32_e32 v49, 2, v45
	ds_read_b128 v[44:47], v44 offset:112
	v_add_f32_e32 v48, v48, v19
	s_waitcnt lgkmcnt(1)
	v_add_f32_e32 v48, v48, v40
	v_add_f32_e32 v48, v48, v41
	v_add_f32_e32 v48, v48, v42
	v_add_f32_e32 v48, v48, v43
	s_waitcnt lgkmcnt(0)
	v_add_f32_e32 v48, v48, v44
	v_add_f32_e32 v48, v48, v45
	v_add_f32_e32 v48, v48, v46
	v_add_f32_e32 v48, v48, v47
	ds_bpermute_b32 v50, v49, v48
	v_readlane_b32 s4, v254, 0
	v_readlane_b32 s5, v254, 1
	s_waitcnt lgkmcnt(0)
	v_add_f32_e32 v50, v48, v50
	v_fmamk_f32 v52, v50, 0xbc800000, v37
	v_fmamk_f32 v51, v50, 0xbc800000, v36
	v_mul_f32_e32 v53, v52, v52
	v_fmac_f32_e32 v53, v51, v51
	v_fmamk_f32 v38, v50, 0xbc800000, v38
	v_fmac_f32_e32 v53, v38, v38
	v_fmac_f32_e32 v39, 0xbc800000, v50
	v_fmac_f32_e32 v53, v39, v39
	v_fmamk_f32 v54, v50, 0xbc800000, v32
	v_fmac_f32_e32 v53, v54, v54
	v_fmamk_f32 v55, v50, 0xbc800000, v33
	v_fmac_f32_e32 v53, v55, v55
	v_fmamk_f32 v34, v50, 0xbc800000, v34
	v_fmac_f32_e32 v53, v34, v34
	v_fmac_f32_e32 v35, 0xbc800000, v50
	v_fmac_f32_e32 v53, v35, v35
	v_fmamk_f32 v56, v50, 0xbc800000, v28
	v_fmac_f32_e32 v53, v56, v56
	v_fmamk_f32 v57, v50, 0xbc800000, v29
	v_fmac_f32_e32 v53, v57, v57
	v_fmamk_f32 v30, v50, 0xbc800000, v30
	v_fmac_f32_e32 v53, v30, v30
	v_fmac_f32_e32 v31, 0xbc800000, v50
	v_fmac_f32_e32 v53, v31, v31
	v_fmamk_f32 v58, v50, 0xbc800000, v24
	v_fmac_f32_e32 v53, v58, v58
	v_fmamk_f32 v59, v50, 0xbc800000, v25
	v_fmac_f32_e32 v53, v59, v59
	v_fmamk_f32 v26, v50, 0xbc800000, v26
	v_fmac_f32_e32 v53, v26, v26
	v_fmac_f32_e32 v27, 0xbc800000, v50
	v_fmac_f32_e32 v53, v27, v27
	v_fmamk_f32 v60, v50, 0xbc800000, v20
	v_fmac_f32_e32 v53, v60, v60
	v_fmamk_f32 v61, v50, 0xbc800000, v21
	v_fmac_f32_e32 v53, v61, v61
	v_fmamk_f32 v22, v50, 0xbc800000, v22
	v_fmac_f32_e32 v53, v22, v22
	v_fmac_f32_e32 v23, 0xbc800000, v50
	v_mul_f32_e32 v48, 0x3c800000, v50
	v_fmac_f32_e32 v53, v23, v23
	v_fmamk_f32 v62, v50, 0xbc800000, v16
	v_fmac_f32_e32 v53, v62, v62
	v_fmac_f32_e32 v17, 0xbc800000, v50
	v_pk_add_f32 v[36:37], v[18:19], v[48:49] op_sel_hi:[1,0] neg_lo:[0,1] neg_hi:[0,1]
	v_fmac_f32_e32 v53, v17, v17
	v_pk_mul_f32 v[18:19], v[36:37], v[36:37]
	v_pk_add_f32 v[32:33], v[40:41], v[48:49] op_sel_hi:[1,0] neg_lo:[0,1] neg_hi:[0,1]
	v_add_f32_e32 v16, v18, v53
	v_add_f32_e32 v16, v19, v16
	v_pk_mul_f32 v[18:19], v[32:33], v[32:33]
	v_pk_add_f32 v[28:29], v[42:43], v[48:49] op_sel_hi:[1,0] neg_lo:[0,1] neg_hi:[0,1]
	v_add_f32_e32 v16, v18, v16
	v_add_f32_e32 v16, v19, v16
	v_pk_mul_f32 v[18:19], v[28:29], v[28:29]
	v_pk_add_f32 v[24:25], v[44:45], v[48:49] op_sel_hi:[1,0] neg_lo:[0,1] neg_hi:[0,1]
	v_add_f32_e32 v16, v18, v16
	v_add_f32_e32 v16, v19, v16
	v_pk_mul_f32 v[18:19], v[24:25], v[24:25]
	s_waitcnt vmcnt(0)
	v_lshlrev_b32_e32 v40, 16, v12
	v_add_f32_e32 v16, v18, v16
	v_add_f32_e32 v16, v19, v16
	v_pk_add_f32 v[18:19], v[46:47], v[48:49] op_sel_hi:[1,0] neg_lo:[0,1] neg_hi:[0,1]
	v_and_b32_e32 v12, 0xffff0000, v12
	v_pk_mul_f32 v[20:21], v[18:19], v[18:19]
	v_mul_f32_e32 v44, 0xbfb8aa3b, v40
	v_add_f32_e32 v16, v20, v16
	v_add_f32_e32 v16, v21, v16
	ds_bpermute_b32 v20, v49, v16
	v_mul_f32_e32 v45, 0xbfb8aa3b, v12
	v_exp_f32_e32 v44, v44
	v_exp_f32_e32 v45, v45
	v_lshlrev_b32_e32 v41, 16, v13
	s_waitcnt lgkmcnt(0)
	v_add_f32_e32 v16, v16, v20
	v_fmamk_f32 v16, v16, 0x3c800000, v219
	v_cmp_gt_f32_e32 vcc, s36, v16
	v_mul_f32_e32 v20, 0x4b800000, v16
	v_add_f32_e32 v44, 1.0, v44
	v_cndmask_b32_e32 v16, v16, v20, vcc
	v_rsq_f32_e32 v16, v16
	v_add_f32_e32 v45, 1.0, v45
	v_rcp_f32_e32 v44, v44
	v_rcp_f32_e32 v45, v45
	v_mul_f32_e32 v20, 0x45800000, v16
	v_cndmask_b32_e32 v16, v16, v20, vcc
	v_and_b32_e32 v13, 0xffff0000, v13
	v_mul_f32_e32 v40, v44, v40
	v_mul_f32_e32 v44, v52, v16
	v_mul_f32_e32 v12, v45, v12
	v_mul_f32_e32 v45, 0xbfb8aa3b, v41
	v_mul_f32_e32 v12, v12, v44
	v_mul_f32_e32 v44, 0xbfb8aa3b, v13
	v_exp_f32_e32 v45, v45
	v_exp_f32_e32 v44, v44
	v_lshlrev_b32_e32 v42, 16, v14
	v_and_b32_e32 v14, 0xffff0000, v14
	v_add_f32_e32 v45, 1.0, v45
	v_add_f32_e32 v44, 1.0, v44
	v_rcp_f32_e32 v45, v45
	v_rcp_f32_e32 v44, v44
	v_mul_f32_e32 v38, v38, v16
	v_mul_f32_e32 v39, v39, v16
	v_mul_f32_e32 v41, v45, v41
	v_mul_f32_e32 v13, v44, v13
	v_mul_f32_e32 v38, v41, v38
	v_mul_f32_e32 v41, 0xbfb8aa3b, v42
	v_mul_f32_e32 v13, v13, v39
	v_mul_f32_e32 v39, 0xbfb8aa3b, v14
	v_exp_f32_e32 v41, v41
	v_exp_f32_e32 v39, v39
	v_lshlrev_b32_e32 v43, 16, v15
	v_and_b32_e32 v15, 0xffff0000, v15
	v_add_f32_e32 v41, 1.0, v41
	v_add_f32_e32 v39, 1.0, v39
	v_rcp_f32_e32 v41, v41
	v_rcp_f32_e32 v39, v39
	v_lshlrev_b64 v[20:21], 11, v[96:97]
	v_lshl_add_u64 v[20:21], s[52:53], 0, v[20:21]
	v_mul_f32_e32 v41, v41, v42
	v_mul_f32_e32 v42, v55, v16
	v_mul_f32_e32 v14, v39, v14
	v_mul_f32_e32 v14, v14, v42
	v_mul_f32_e32 v42, 0xbfb8aa3b, v15
	v_mul_f32_e32 v39, 0xbfb8aa3b, v43
	v_exp_f32_e32 v42, v42
	v_exp_f32_e32 v39, v39
	v_lshl_add_u64 v[20:21], v[20:21], 0, s[88:89]
	v_mul_f32_e32 v46, v51, v16
	v_add_f32_e32 v42, 1.0, v42
	v_add_f32_e32 v39, 1.0, v39
	v_rcp_f32_e32 v42, v42
	v_rcp_f32_e32 v39, v39
	v_mul_f32_e32 v35, v35, v16
	v_lshl_add_u64 v[20:21], v[20:21], 0, v[184:185]
	v_mul_f32_e32 v15, v42, v15
	v_mul_f32_e32 v40, v40, v46
	v_mul_f32_e32 v44, v54, v16
	v_mul_f32_e32 v34, v34, v16
	v_mul_f32_e32 v39, v39, v43
	v_mul_f32_e32 v15, v15, v35
	v_cvt_pk_bf16_f32 v12, v40, v12
	v_mul_f32_e32 v41, v41, v44
	v_mul_f32_e32 v34, v39, v34
	v_cvt_pk_bf16_f32 v13, v38, v13
	v_cvt_pk_bf16_f32 v14, v41, v14
	v_cvt_pk_bf16_f32 v15, v34, v15
	global_store_dwordx4 v[20:21], v[12:15], off
	v_mul_f32_e32 v30, v30, v16
	v_mul_f32_e32 v26, v26, v16
	v_lshlrev_b32_e32 v12, 16, v8
	v_and_b32_e32 v8, 0xffff0000, v8
	v_mul_f32_e32 v34, 0xbfb8aa3b, v12
	v_mul_f32_e32 v35, 0xbfb8aa3b, v8
	v_exp_f32_e32 v34, v34
	v_exp_f32_e32 v35, v35
	v_lshlrev_b32_e32 v13, 16, v9
	v_and_b32_e32 v9, 0xffff0000, v9
	v_add_f32_e32 v34, 1.0, v34
	v_add_f32_e32 v35, 1.0, v35
	v_rcp_f32_e32 v34, v34
	v_rcp_f32_e32 v35, v35
	v_lshlrev_b32_e32 v14, 16, v10
	v_and_b32_e32 v10, 0xffff0000, v10
	v_mul_f32_e32 v12, v34, v12
	v_mul_f32_e32 v34, v57, v16
	v_mul_f32_e32 v8, v35, v8
	v_mul_f32_e32 v35, 0xbfb8aa3b, v13
	v_exp_f32_e32 v35, v35
	v_mul_f32_e32 v8, v8, v34
	v_mul_f32_e32 v34, 0xbfb8aa3b, v9
	v_exp_f32_e32 v34, v34
	v_add_f32_e32 v35, 1.0, v35
	v_rcp_f32_e32 v35, v35
	v_lshlrev_b32_e32 v15, 16, v11
	v_add_f32_e32 v34, 1.0, v34
	v_rcp_f32_e32 v34, v34
	v_mul_f32_e32 v13, v35, v13
	v_mul_f32_e32 v13, v13, v30
	v_mul_f32_e32 v30, v31, v16
	v_mul_f32_e32 v9, v34, v9
	v_mul_f32_e32 v31, 0xbfb8aa3b, v14
	v_mul_f32_e32 v9, v9, v30
	v_mul_f32_e32 v30, 0xbfb8aa3b, v10
	v_exp_f32_e32 v31, v31
	v_exp_f32_e32 v30, v30
	v_and_b32_e32 v11, 0xffff0000, v11
	v_mul_f32_e32 v38, v56, v16
	v_add_f32_e32 v31, 1.0, v31
	v_add_f32_e32 v30, 1.0, v30
	v_rcp_f32_e32 v31, v31
	v_rcp_f32_e32 v30, v30
	v_mul_f32_e32 v12, v12, v38
	v_mul_f32_e32 v34, v58, v16
	v_mul_f32_e32 v14, v31, v14
	v_mul_f32_e32 v31, v59, v16
	v_mul_f32_e32 v10, v30, v10
	v_mul_f32_e32 v30, 0xbfb8aa3b, v15
	v_exp_f32_e32 v30, v30
	v_mul_f32_e32 v10, v10, v31
	v_mul_f32_e32 v31, 0xbfb8aa3b, v11
	v_exp_f32_e32 v31, v31
	v_add_f32_e32 v30, 1.0, v30
	v_rcp_f32_e32 v30, v30
	v_cvt_pk_bf16_f32 v8, v12, v8
	v_add_f32_e32 v31, 1.0, v31
	v_rcp_f32_e32 v31, v31
	v_mul_f32_e32 v15, v30, v15
	v_mul_f32_e32 v15, v15, v26
	v_mul_f32_e32 v26, v27, v16
	v_mul_f32_e32 v11, v31, v11
	v_mul_f32_e32 v11, v11, v26
	v_mul_f32_e32 v14, v14, v34
	v_cvt_pk_bf16_f32 v9, v13, v9
	v_cvt_pk_bf16_f32 v10, v14, v10
	v_cvt_pk_bf16_f32 v11, v15, v11
	global_store_dwordx4 v[20:21], v[8:11], off offset:16
	v_mul_f32_e32 v14, v60, v16
	s_nop 0
	v_lshlrev_b32_e32 v8, 16, v4
	v_and_b32_e32 v4, 0xffff0000, v4
	v_mul_f32_e32 v12, 0xbfb8aa3b, v8
	v_mul_f32_e32 v13, 0xbfb8aa3b, v4
	v_exp_f32_e32 v12, v12
	v_exp_f32_e32 v13, v13
	v_lshlrev_b32_e32 v9, 16, v5
	v_and_b32_e32 v5, 0xffff0000, v5
	v_add_f32_e32 v12, 1.0, v12
	v_add_f32_e32 v13, 1.0, v13
	v_rcp_f32_e32 v12, v12
	v_rcp_f32_e32 v13, v13
	v_lshlrev_b32_e32 v10, 16, v6
	v_and_b32_e32 v6, 0xffff0000, v6
	v_mul_f32_e32 v8, v12, v8
	v_mul_f32_e32 v12, v61, v16
	v_mul_f32_e32 v4, v13, v4
	v_mul_f32_e32 v13, 0xbfb8aa3b, v9
	v_mul_f32_e32 v4, v4, v12
	v_mul_f32_e32 v12, 0xbfb8aa3b, v5
	v_exp_f32_e32 v13, v13
	v_exp_f32_e32 v12, v12
	v_lshlrev_b32_e32 v11, 16, v7
	v_and_b32_e32 v7, 0xffff0000, v7
	v_add_f32_e32 v13, 1.0, v13
	v_add_f32_e32 v12, 1.0, v12
	v_rcp_f32_e32 v13, v13
	v_rcp_f32_e32 v12, v12
	v_mul_f32_e32 v8, v8, v14
	v_mul_f32_e32 v14, v22, v16
	v_mul_f32_e32 v9, v13, v9
	v_mul_f32_e32 v13, v23, v16
	v_mul_f32_e32 v5, v12, v5
	v_mul_f32_e32 v12, 0xbfb8aa3b, v10
	v_mul_f32_e32 v5, v5, v13
	v_mul_f32_e32 v13, 0xbfb8aa3b, v6
	v_exp_f32_e32 v12, v12
	v_exp_f32_e32 v13, v13
	v_mul_f32_e32 v9, v9, v14
	v_mul_f32_e32 v14, v62, v16
	v_add_f32_e32 v12, 1.0, v12
	v_add_f32_e32 v13, 1.0, v13
	v_rcp_f32_e32 v12, v12
	v_rcp_f32_e32 v13, v13
	v_cvt_pk_bf16_f32 v4, v8, v4
	v_cvt_pk_bf16_f32 v5, v9, v5
	v_mul_f32_e32 v10, v12, v10
	v_mul_f32_e32 v12, v17, v16
	v_mul_f32_e32 v6, v13, v6
	v_mul_f32_e32 v13, 0xbfb8aa3b, v11
	v_mul_f32_e32 v6, v6, v12
	v_mul_f32_e32 v12, 0xbfb8aa3b, v7
	v_exp_f32_e32 v13, v13
	v_exp_f32_e32 v12, v12
	v_mul_f32_e32 v10, v10, v14
	v_mul_f32_e32 v14, v36, v16
	v_add_f32_e32 v13, 1.0, v13
	v_add_f32_e32 v12, 1.0, v12
	v_rcp_f32_e32 v13, v13
	v_rcp_f32_e32 v12, v12
	v_cvt_pk_bf16_f32 v6, v10, v6
	v_mul_f32_e32 v10, v32, v16
	v_mul_f32_e32 v11, v13, v11
	v_mul_f32_e32 v13, v37, v16
	v_mul_f32_e32 v7, v12, v7
	v_mul_f32_e32 v7, v7, v13
	v_mul_f32_e32 v11, v11, v14
	v_cvt_pk_bf16_f32 v7, v11, v7
	global_store_dwordx4 v[20:21], v[4:7], off offset:32
	s_nop 1
	v_lshlrev_b32_e32 v4, 16, v0
	v_and_b32_e32 v0, 0xffff0000, v0
	v_mul_f32_e32 v8, 0xbfb8aa3b, v4
	v_mul_f32_e32 v9, 0xbfb8aa3b, v0
	v_exp_f32_e32 v8, v8
	v_exp_f32_e32 v9, v9
	v_lshlrev_b32_e32 v5, 16, v1
	v_and_b32_e32 v1, 0xffff0000, v1
	v_add_f32_e32 v8, 1.0, v8
	v_add_f32_e32 v9, 1.0, v9
	v_rcp_f32_e32 v8, v8
	v_rcp_f32_e32 v9, v9
	v_lshlrev_b32_e32 v6, 16, v2
	v_and_b32_e32 v2, 0xffff0000, v2
	v_mul_f32_e32 v4, v8, v4
	v_mul_f32_e32 v8, v33, v16
	v_mul_f32_e32 v0, v9, v0
	v_mul_f32_e32 v9, 0xbfb8aa3b, v5
	v_mul_f32_e32 v0, v0, v8
	v_mul_f32_e32 v8, 0xbfb8aa3b, v1
	v_exp_f32_e32 v9, v9
	v_exp_f32_e32 v8, v8
	v_lshlrev_b32_e32 v7, 16, v3
	v_and_b32_e32 v3, 0xffff0000, v3
	v_add_f32_e32 v9, 1.0, v9
	v_add_f32_e32 v8, 1.0, v8
	v_rcp_f32_e32 v9, v9
	v_rcp_f32_e32 v8, v8
	v_mul_f32_e32 v4, v4, v10
	v_mul_f32_e32 v10, v28, v16
	v_mul_f32_e32 v5, v9, v5
	v_mul_f32_e32 v9, v29, v16
	v_mul_f32_e32 v1, v8, v1
	v_mul_f32_e32 v8, 0xbfb8aa3b, v6
	v_mul_f32_e32 v1, v1, v9
	v_mul_f32_e32 v9, 0xbfb8aa3b, v2
	v_exp_f32_e32 v8, v8
	v_exp_f32_e32 v9, v9
	v_mul_f32_e32 v5, v5, v10
	v_mul_f32_e32 v10, v24, v16
	v_add_f32_e32 v8, 1.0, v8
	v_add_f32_e32 v9, 1.0, v9
	v_rcp_f32_e32 v8, v8
	v_rcp_f32_e32 v9, v9
	v_cvt_pk_bf16_f32 v0, v4, v0
	v_cvt_pk_bf16_f32 v1, v5, v1
	v_mul_f32_e32 v6, v8, v6
	v_mul_f32_e32 v8, v25, v16
	v_mul_f32_e32 v2, v9, v2
	v_mul_f32_e32 v9, 0xbfb8aa3b, v7
	v_mul_f32_e32 v2, v2, v8
	v_mul_f32_e32 v8, 0xbfb8aa3b, v3
	v_exp_f32_e32 v9, v9
	v_exp_f32_e32 v8, v8
	v_mul_f32_e32 v6, v6, v10
	v_mul_f32_e32 v10, v18, v16
	v_add_f32_e32 v9, 1.0, v9
	v_add_f32_e32 v8, 1.0, v8
	v_rcp_f32_e32 v9, v9
	v_rcp_f32_e32 v8, v8
	v_cvt_pk_bf16_f32 v2, v6, v2
	v_mul_f32_e32 v7, v9, v7
	v_mul_f32_e32 v9, v19, v16
	v_mul_f32_e32 v3, v8, v3
	v_mul_f32_e32 v3, v3, v9
	v_mul_f32_e32 v7, v7, v10
	v_cvt_pk_bf16_f32 v3, v7, v3
	global_store_dwordx4 v[20:21], v[0:3], off offset:48
	s_barrier
	s_load_dword s20, s[4:5], 0x0
	s_waitcnt lgkmcnt(0)
	s_lshl_b32 s20, s20, 1
	s_add_i32 s38, s20, s38
	s_cmp_ge_i32 s38, s30
	s_cbranch_scc1 .LBB0_202

.LBB0_198:
	s_and_b32 s26, s26, 3
	s_or_b32 s28, s26, s31
	v_readlane_b32 s40, v253, 48
	v_ashrrev_i32_e32 v64, 1, v100
	s_ashr_i32 s29, s28, 31
	s_nop 1
	s_waitcnt vmcnt(0)
	v_add_u32_e32 v0, s20, v64
	s_lshl_b64 s[28:29], s[28:29], 2
	v_ashrrev_i32_e32 v1, 31, v0
	v_readlane_b32 s48, v253, 16
	v_readlane_b32 s41, v253, 49
	s_add_u32 s28, s40, s28
	v_lshlrev_b64 v[0:1], 12, v[0:1]
	v_readlane_b32 s49, v253, 17
	s_addc_u32 s29, s41, s29
	v_and_b32_e32 v62, 1, v100
	v_lshl_add_u64 v[0:1], s[48:49], 0, v[0:1]
	s_lshl_b32 s88, s26, 7
	v_lshlrev_b32_e32 v184, 6, v62
	v_lshl_add_u64 v[0:1], v[0:1], 0, s[88:89]
	v_lshl_add_u64 v[12:13], v[0:1], 0, v[184:185]
	global_load_dwordx4 v[0:3], v[12:13], off
	global_load_dwordx4 v[4:7], v[12:13], off offset:16
	global_load_dwordx4 v[8:11], v[12:13], off offset:32
	global_load_dwordx4 v[26:29], v[12:13], off offset:48
	global_load_dwordx4 v[168:171], v[12:13], off offset:560
	global_load_dwordx4 v[172:175], v[12:13], off offset:544
	global_load_dwordx4 v[176:179], v[12:13], off offset:528
	global_load_dwordx4 v[180:183], v[12:13], off offset:512
	global_load_dwordx4 v[194:197], v[12:13], off offset:1024
	global_load_dwordx4 v[198:201], v[12:13], off offset:1040
	global_load_dwordx4 v[202:205], v[12:13], off offset:1072
	global_load_dwordx4 v[206:209], v[12:13], off offset:1056
	global_load_dword v65, v185, s[28:29]
	global_load_dword v63, v185, s[28:29] offset:16
	v_cndmask_b32_e64 v15, 0, 1, s[22:23]
	v_add_u32_e32 v14, s27, v64
	v_cmp_ne_u32_e64 s[36:37], 1, v15
	v_ashrrev_i32_e32 v15, 31, v14
	v_readlane_b32 s60, v253, 28
	v_readlane_b32 s61, v253, 29
	v_lshlrev_b64 v[14:15], 8, v[14:15]
	v_readlane_b32 s50, v253, 18
	v_lshl_add_u64 v[14:15], s[60:61], 0, v[14:15]
	v_readlane_b32 s51, v253, 19
	v_readlane_b32 s52, v253, 20
	v_readlane_b32 s53, v253, 21
	v_readlane_b32 s54, v253, 22
	v_readlane_b32 s55, v253, 23
	v_readlane_b32 s56, v253, 24
	v_readlane_b32 s57, v253, 25
	v_readlane_b32 s58, v253, 26
	v_readlane_b32 s59, v253, 27
	s_nop 1
	v_lshl_add_u64 v[18:19], v[14:15], 0, v[184:185]
	s_andn2_b64 vcc, exec, s[22:23]
	v_readlane_b32 s42, v253, 50
	v_readlane_b32 s43, v253, 51
	v_readlane_b32 s44, v253, 52
	v_readlane_b32 s45, v253, 53
	v_readlane_b32 s46, v253, 54
	v_readlane_b32 s47, v253, 55
	s_waitcnt vmcnt(0)
	v_lshlrev_b32_e32 v58, 16, v0
	v_and_b32_e32 v59, 0xffff0000, v0
	v_lshlrev_b32_e32 v56, 16, v1
	v_and_b32_e32 v57, 0xffff0000, v1
	v_lshlrev_b32_e32 v54, 16, v2
	v_and_b32_e32 v55, 0xffff0000, v2
	v_lshlrev_b32_e32 v52, 16, v3
	v_and_b32_e32 v53, 0xffff0000, v3
	v_lshlrev_b32_e32 v50, 16, v4
	v_and_b32_e32 v51, 0xffff0000, v4
	v_lshlrev_b32_e32 v48, 16, v5
	v_and_b32_e32 v49, 0xffff0000, v5
	v_lshlrev_b32_e32 v46, 16, v6
	v_and_b32_e32 v47, 0xffff0000, v6
	v_lshlrev_b32_e32 v30, 16, v7
	v_lshlrev_b32_e32 v24, 16, v8
	v_and_b32_e32 v25, 0xffff0000, v8
	v_lshlrev_b32_e32 v22, 16, v9
	v_and_b32_e32 v23, 0xffff0000, v9
	v_lshlrev_b32_e32 v20, 16, v10
	v_and_b32_e32 v21, 0xffff0000, v10
	v_lshlrev_b32_e32 v16, 16, v11
	v_and_b32_e32 v17, 0xffff0000, v11
	v_lshlrev_b32_e32 v14, 16, v26
	v_and_b32_e32 v15, 0xffff0000, v26
	v_lshlrev_b32_e32 v10, 16, v27
	v_and_b32_e32 v11, 0xffff0000, v27
	v_lshlrev_b32_e32 v8, 16, v28
	v_and_b32_e32 v9, 0xffff0000, v28
	v_lshlrev_b32_e32 v28, 16, v29
	v_and_b32_e32 v27, 0xffff0000, v7
	v_and_b32_e32 v26, 0xffff0000, v29
	s_cbranch_vccnz .LBB0_200
	global_load_dwordx4 v[4:7], v[18:19], off offset:48
	global_load_dwordx4 v[42:45], v[18:19], off offset:32
	global_load_dwordx4 v[38:41], v[18:19], off offset:16
	global_load_dwordx4 v[34:37], v[18:19], off
	global_load_dwordx4 v[0:3], v[18:19], off offset:176
	global_load_dwordx4 v[66:69], v[18:19], off offset:160
	global_load_dwordx4 v[70:73], v[18:19], off offset:144
	global_load_dwordx4 v[74:77], v[18:19], off offset:128
	v_mov_b32_e32 v29, v26
	v_mov_b32_e32 v31, v27
	s_waitcnt vmcnt(0)
	v_pk_mul_f32 v[32:33], v[74:75], v[24:25]
	s_nop 0
	v_pk_fma_f32 v[32:33], v[34:35], v[58:59], v[32:33] neg_lo:[0,0,1] neg_hi:[0,0,1]
	v_pk_mul_f32 v[58:59], v[74:75], v[58:59]
	s_nop 0
	v_pk_fma_f32 v[24:25], v[34:35], v[24:25], v[58:59]
	v_pk_mul_f32 v[34:35], v[76:77], v[22:23]
	v_mov_b32_e32 v58, v32
	v_pk_fma_f32 v[34:35], v[36:37], v[56:57], v[34:35] neg_lo:[0,0,1] neg_hi:[0,0,1]
	v_pk_mul_f32 v[56:57], v[76:77], v[56:57]
	v_mov_b32_e32 v59, v33
	v_pk_fma_f32 v[22:23], v[36:37], v[22:23], v[56:57]
	v_pk_mul_f32 v[36:37], v[70:71], v[20:21]
	v_mov_b32_e32 v56, v34
	v_pk_fma_f32 v[36:37], v[38:39], v[54:55], v[36:37] neg_lo:[0,0,1] neg_hi:[0,0,1]
	v_pk_mul_f32 v[54:55], v[70:71], v[54:55]
	v_mov_b32_e32 v57, v35
	v_pk_fma_f32 v[20:21], v[38:39], v[20:21], v[54:55]
	v_pk_mul_f32 v[38:39], v[72:73], v[16:17]
	v_mov_b32_e32 v54, v36
	v_pk_fma_f32 v[38:39], v[40:41], v[52:53], v[38:39] neg_lo:[0,0,1] neg_hi:[0,0,1]
	v_pk_mul_f32 v[52:53], v[72:73], v[52:53]
	v_mov_b32_e32 v55, v37
	v_pk_fma_f32 v[16:17], v[40:41], v[16:17], v[52:53]
	v_pk_mul_f32 v[40:41], v[66:67], v[14:15]
	v_mov_b32_e32 v52, v38
	v_pk_fma_f32 v[40:41], v[42:43], v[50:51], v[40:41] neg_lo:[0,0,1] neg_hi:[0,0,1]
	v_pk_mul_f32 v[50:51], v[66:67], v[50:51]
	v_mov_b32_e32 v53, v39
	v_pk_fma_f32 v[14:15], v[42:43], v[14:15], v[50:51]
	v_pk_mul_f32 v[42:43], v[68:69], v[10:11]
	v_mov_b32_e32 v50, v40
	v_pk_fma_f32 v[42:43], v[44:45], v[48:49], v[42:43] neg_lo:[0,0,1] neg_hi:[0,0,1]
	v_pk_mul_f32 v[48:49], v[68:69], v[48:49]
	v_mov_b32_e32 v51, v41
	v_pk_fma_f32 v[10:11], v[44:45], v[10:11], v[48:49]
	v_pk_mul_f32 v[44:45], v[0:1], v[8:9]
	v_pk_mul_f32 v[0:1], v[0:1], v[46:47]
	v_pk_fma_f32 v[44:45], v[4:5], v[46:47], v[44:45] neg_lo:[0,0,1] neg_hi:[0,0,1]
	v_pk_fma_f32 v[8:9], v[4:5], v[8:9], v[0:1]
	v_pk_mul_f32 v[0:1], v[2:3], v[28:29]
	v_mul_f32_e32 v4, v2, v30
	v_mov_b32_e32 v2, v7
	v_pk_mul_f32 v[2:3], v[2:3], v[26:27]
	v_pk_fma_f32 v[0:1], v[6:7], v[30:31], v[0:1] neg_lo:[0,0,1] neg_hi:[0,0,1]
	v_mul_f32_e32 v6, v6, v28
	v_mov_b32_e32 v7, v2
	v_mov_b32_e32 v5, v3
	v_pk_add_f32 v[28:29], v[6:7], v[4:5]
	v_mov_b32_e32 v48, v42
	v_mov_b32_e32 v49, v43
	v_mov_b32_e32 v46, v44
	v_mov_b32_e32 v47, v45
	v_mov_b32_e32 v30, v0
	v_mov_b32_e32 v27, v1
	v_mov_b32_e32 v26, v29
.LBB0_200:
	v_lshlrev_b32_e32 v0, 5, v62
	v_mul_f32_e32 v1, 0x3e000000, v58
	v_mul_f32_e32 v2, 0x3e000000, v59
	v_mul_f32_e32 v3, 0x3e000000, v56
	v_mul_f32_e32 v39, 0x3e000000, v14
	v_mul_f32_e32 v15, 0x3e000000, v15
	v_lshl_add_u32 v14, v0, 1, s2
	s_movk_i32 s4, 0x90
	s_lshl_b32 s22, s26, 6
	v_mul_f32_e32 v4, 0x3e000000, v57
	v_mul_f32_e32 v5, 0x3e000000, v54
	v_mul_f32_e32 v6, 0x3e000000, v55
	v_mul_f32_e32 v7, 0x3e000000, v52
	v_mul_f32_e32 v29, 0x3e000000, v53
	v_mul_f32_e32 v37, 0x3e000000, v16
	v_mul_f32_e32 v38, 0x3e000000, v17
	v_mad_u64_u32 v[16:17], s[26:27], v64, s4, v[14:15]
	v_cvt_pk_bf16_f32 v0, v1, v2
	v_cvt_pk_bf16_f32 v1, v3, v4
	v_cvt_pk_bf16_f32 v2, v5, v6
	v_cvt_pk_bf16_f32 v3, v7, v29
	v_mul_f32_e32 v31, 0x3e000000, v50
	v_mul_f32_e32 v32, 0x3e000000, v51
	v_mul_f32_e32 v33, 0x3e000000, v48
	v_mul_f32_e32 v34, 0x3e000000, v49
	v_mul_f32_e32 v35, 0x3e000000, v46
	v_mul_f32_e32 v36, 0x3e000000, v47
	v_mul_f32_e32 v30, 0x3e000000, v30
	v_mul_f32_e32 v27, 0x3e000000, v27
	ds_write_b128 v16, v[0:3]
	v_cvt_pk_bf16_f32 v0, v31, v32
	v_cvt_pk_bf16_f32 v1, v33, v34
	v_cvt_pk_bf16_f32 v2, v35, v36
	v_cvt_pk_bf16_f32 v3, v30, v27
	v_mul_f32_e32 v24, 0x3e000000, v24
	v_mul_f32_e32 v25, 0x3e000000, v25
	v_mul_f32_e32 v22, 0x3e000000, v22
	v_mul_f32_e32 v23, 0x3e000000, v23
	v_mul_f32_e32 v20, 0x3e000000, v20
	v_mul_f32_e32 v21, 0x3e000000, v21
	ds_write_b128 v16, v[0:3] offset:16
	v_cvt_pk_bf16_f32 v0, v24, v25
	v_cvt_pk_bf16_f32 v1, v22, v23
	v_cvt_pk_bf16_f32 v2, v20, v21
	v_cvt_pk_bf16_f32 v3, v37, v38
	v_mul_f32_e32 v10, 0x3e000000, v10
	v_mul_f32_e32 v11, 0x3e000000, v11
	v_mul_f32_e32 v8, 0x3e000000, v8
	v_mul_f32_e32 v9, 0x3e000000, v9
	v_mul_f32_e32 v28, 0x3e000000, v28
	v_mul_f32_e32 v26, 0x3e000000, v26
	ds_write_b128 v16, v[0:3] offset:32
	v_cvt_pk_bf16_f32 v0, v39, v15
	v_cvt_pk_bf16_f32 v1, v10, v11
	v_cvt_pk_bf16_f32 v2, v8, v9
	v_cvt_pk_bf16_f32 v3, v28, v26
	ds_write_b128 v16, v[0:3] offset:48
	s_mov_b32 s5, 0x3f2aaaab
	s_mov_b32 s6, 0x3f317218
	s_mov_b32 s7, 0x33800000
	s_and_b64 vcc, exec, s[36:37]
	s_waitcnt vmcnt(0)
	v_lshlrev_b32_e32 v26, 16, v169
	v_lshlrev_b32_e32 v24, 16, v175
	v_lshlrev_b32_e32 v40, 16, v176
	v_lshlrev_b32_e32 v48, 16, v180
	v_and_b32_e32 v49, 0xffff0000, v180
	v_lshlrev_b32_e32 v46, 16, v181
	v_and_b32_e32 v47, 0xffff0000, v181
	v_lshlrev_b32_e32 v44, 16, v182
	v_and_b32_e32 v45, 0xffff0000, v182
	v_lshlrev_b32_e32 v42, 16, v183
	v_and_b32_e32 v43, 0xffff0000, v183
	v_and_b32_e32 v41, 0xffff0000, v176
	v_lshlrev_b32_e32 v38, 16, v177
	v_and_b32_e32 v39, 0xffff0000, v177
	v_lshlrev_b32_e32 v36, 16, v178
	v_and_b32_e32 v37, 0xffff0000, v178
	v_lshlrev_b32_e32 v34, 16, v179
	v_lshlrev_b32_e32 v20, 16, v172
	v_and_b32_e32 v21, 0xffff0000, v172
	v_lshlrev_b32_e32 v8, 16, v173
	v_and_b32_e32 v9, 0xffff0000, v173
	v_lshlrev_b32_e32 v22, 16, v174
	v_and_b32_e32 v23, 0xffff0000, v174
	v_and_b32_e32 v25, 0xffff0000, v175
	v_lshlrev_b32_e32 v10, 16, v168
	v_and_b32_e32 v11, 0xffff0000, v168
	v_and_b32_e32 v27, 0xffff0000, v169
	v_lshlrev_b32_e32 v28, 16, v170
	v_and_b32_e32 v29, 0xffff0000, v170
	v_lshlrev_b32_e32 v32, 16, v171
	v_and_b32_e32 v31, 0xffff0000, v179
	v_and_b32_e32 v30, 0xffff0000, v171
	s_cbranch_vccnz .LBB0_193
	global_load_dwordx4 v[4:7], v[18:19], off offset:48
	global_load_dwordx4 v[58:61], v[18:19], off offset:32
	global_load_dwordx4 v[54:57], v[18:19], off offset:16
	global_load_dwordx4 v[50:53], v[18:19], off
	global_load_dwordx4 v[0:3], v[18:19], off offset:176
	global_load_dwordx4 v[66:69], v[18:19], off offset:160
	global_load_dwordx4 v[70:73], v[18:19], off offset:144
	global_load_dwordx4 v[74:77], v[18:19], off offset:128
	v_mov_b32_e32 v33, v30
	v_mov_b32_e32 v35, v31
	s_waitcnt vmcnt(0)
	v_pk_mul_f32 v[18:19], v[74:75], v[20:21]
	s_nop 0
	v_pk_fma_f32 v[18:19], v[50:51], v[48:49], v[18:19] neg_lo:[0,0,1] neg_hi:[0,0,1]
	v_pk_mul_f32 v[48:49], v[74:75], v[48:49]
	s_nop 0
	v_pk_fma_f32 v[20:21], v[50:51], v[20:21], v[48:49]
	v_pk_mul_f32 v[48:49], v[76:77], v[8:9]
	s_nop 0
	v_pk_fma_f32 v[50:51], v[52:53], v[46:47], v[48:49] neg_lo:[0,0,1] neg_hi:[0,0,1]
	v_pk_mul_f32 v[46:47], v[76:77], v[46:47]
	v_mov_b32_e32 v48, v18
	v_pk_fma_f32 v[8:9], v[52:53], v[8:9], v[46:47]
	v_pk_mul_f32 v[46:47], v[70:71], v[22:23]
	v_mov_b32_e32 v49, v19
	v_pk_fma_f32 v[52:53], v[54:55], v[44:45], v[46:47] neg_lo:[0,0,1] neg_hi:[0,0,1]
	v_pk_mul_f32 v[44:45], v[70:71], v[44:45]
	v_mov_b32_e32 v46, v50
	v_pk_fma_f32 v[22:23], v[54:55], v[22:23], v[44:45]
	v_pk_mul_f32 v[44:45], v[72:73], v[24:25]
	v_mov_b32_e32 v47, v51
	v_pk_fma_f32 v[54:55], v[56:57], v[42:43], v[44:45] neg_lo:[0,0,1] neg_hi:[0,0,1]
	v_pk_mul_f32 v[42:43], v[72:73], v[42:43]
	v_mov_b32_e32 v44, v52
	v_pk_fma_f32 v[24:25], v[56:57], v[24:25], v[42:43]
	v_pk_mul_f32 v[42:43], v[66:67], v[10:11]
	v_mov_b32_e32 v45, v53
	v_pk_fma_f32 v[56:57], v[58:59], v[40:41], v[42:43] neg_lo:[0,0,1] neg_hi:[0,0,1]
	v_pk_mul_f32 v[40:41], v[66:67], v[40:41]
	v_mov_b32_e32 v42, v54
	v_pk_fma_f32 v[10:11], v[58:59], v[10:11], v[40:41]
	v_pk_mul_f32 v[40:41], v[68:69], v[26:27]
	v_mov_b32_e32 v43, v55
	v_pk_fma_f32 v[58:59], v[60:61], v[38:39], v[40:41] neg_lo:[0,0,1] neg_hi:[0,0,1]
	v_pk_mul_f32 v[38:39], v[68:69], v[38:39]
	v_mov_b32_e32 v40, v56
	v_pk_fma_f32 v[26:27], v[60:61], v[26:27], v[38:39]
	v_pk_mul_f32 v[38:39], v[0:1], v[28:29]
	v_pk_mul_f32 v[0:1], v[0:1], v[36:37]
	v_pk_fma_f32 v[60:61], v[4:5], v[36:37], v[38:39] neg_lo:[0,0,1] neg_hi:[0,0,1]
	v_pk_fma_f32 v[28:29], v[4:5], v[28:29], v[0:1]
	v_pk_mul_f32 v[0:1], v[2:3], v[32:33]
	v_mul_f32_e32 v4, v2, v34
	v_mov_b32_e32 v2, v7
	v_pk_mul_f32 v[2:3], v[2:3], v[30:31]
	v_pk_fma_f32 v[0:1], v[6:7], v[34:35], v[0:1] neg_lo:[0,0,1] neg_hi:[0,0,1]
	v_mul_f32_e32 v6, v6, v32
	v_mov_b32_e32 v7, v2
	v_mov_b32_e32 v5, v3
	v_pk_add_f32 v[32:33], v[6:7], v[4:5]
	v_mov_b32_e32 v41, v57
	v_mov_b32_e32 v38, v58
	v_mov_b32_e32 v39, v59
	v_mov_b32_e32 v36, v60
	v_mov_b32_e32 v37, v61
	v_mov_b32_e32 v34, v0
	v_mov_b32_e32 v31, v1
	v_mov_b32_e32 v30, v33
	s_branch .LBB0_193
